# P8 start stagger: 8 groups x 1.5us instead of 2 groups x 6us
# speedup vs baseline: 1.0091x; 1.0004x over previous
.LBB0_1307:
	v_add_f32_e32 v2, v96, v97
	v_add_f32_e32 v2, v98, v2
	v_add_f32_e32 v2, v99, v2
	v_add_f32_e32 v2, v100, v2
	v_add_f32_e32 v2, v101, v2
	v_add_f32_e32 v2, v102, v2
	v_add_f32_e32 v2, v103, v2
	v_add_f32_e32 v2, v104, v2
	v_add_f32_e32 v2, v105, v2
	v_add_f32_e32 v2, v106, v2
	v_add_f32_e32 v2, v107, v2
	v_add_f32_e32 v2, v108, v2
	v_add_f32_e32 v2, v109, v2
	v_add_f32_e32 v2, v110, v2
	v_add_f32_e32 v2, v111, v2
	v_add_f32_e32 v2, v64, v2
	v_add_f32_e32 v2, v65, v2
	v_add_f32_e32 v2, v66, v2
	v_add_f32_e32 v2, v67, v2
	v_add_f32_e32 v2, v68, v2
	v_add_f32_e32 v2, v69, v2
	v_add_f32_e32 v2, v70, v2
	v_add_f32_e32 v2, v71, v2
	v_add_f32_e32 v2, v72, v2
	v_add_f32_e32 v2, v73, v2
	v_add_f32_e32 v2, v74, v2
	v_add_f32_e32 v2, v75, v2
	v_add_f32_e32 v2, v76, v2
	v_add_f32_e32 v2, v77, v2
	v_add_f32_e32 v2, v78, v2
	v_add_f32_e32 v2, v79, v2
	v_add_f32_e32 v2, v144, v2
	v_cvt_pk_bf16_f32 v4, v96, v97
	v_cvt_pk_bf16_f32 v5, v98, v99
	v_cvt_pk_bf16_f32 v6, v100, v101
	v_cvt_pk_bf16_f32 v7, v102, v103
	v_cvt_pk_bf16_f32 v8, v104, v105
	v_cvt_pk_bf16_f32 v9, v106, v107
	v_cvt_pk_bf16_f32 v10, v108, v109
	v_cvt_pk_bf16_f32 v11, v110, v111
	v_cvt_pk_bf16_f32 v64, v64, v65
	v_cvt_pk_bf16_f32 v65, v66, v67
	v_cvt_pk_bf16_f32 v66, v68, v69
	v_cvt_pk_bf16_f32 v67, v70, v71
	v_cvt_pk_bf16_f32 v68, v72, v73
	v_cvt_pk_bf16_f32 v69, v74, v75
	v_cvt_pk_bf16_f32 v70, v76, v77
	v_cvt_pk_bf16_f32 v71, v78, v79
	s_cmp_lg_u32 0, -1
	s_cselect_b32 s6, 0, 0
	s_add_i32 s6, s6, 0x12000
	v_add_u32_e32 v3, s6, v240
	v_add3_u32 v3, v3, v235, v241
	ds_read_b64_tr_b16 v[72:73],v3 offset:0
	ds_read_b64_tr_b16 v[74:75],v3 offset:512
	ds_read_b64_tr_b16 v[76:77],v3 offset:1024
	ds_read_b64_tr_b16 v[78:79],v3 offset:1536
	ds_read_b64_tr_b16 v[80:81],v3 offset:2048
	ds_read_b64_tr_b16 v[82:83],v3 offset:2560
	ds_read_b64_tr_b16 v[84:85],v3 offset:3072
	ds_read_b64_tr_b16 v[86:87],v3 offset:3584
	s_waitcnt lgkmcnt(0)
	s_nop 0
	v_mfma_f32_32x32x16_bf16 v[48:63], v[4:7], v[72:75], v[48:63]
	ds_read_b64_tr_b16 v[72:73],v3 offset:4096
	ds_read_b64_tr_b16 v[74:75],v3 offset:4608
	v_mfma_f32_32x32x16_bf16 v[48:63], v[8:11], v[76:79], v[48:63]
	ds_read_b64_tr_b16 v[76:77],v3 offset:5120
	ds_read_b64_tr_b16 v[78:79],v3 offset:5632
	v_mfma_f32_32x32x16_bf16 v[48:63], v[64:67], v[80:83], v[48:63]
	ds_read_b64_tr_b16 v[80:81],v3 offset:6144
	ds_read_b64_tr_b16 v[82:83],v3 offset:6656
	ds_read_b64_tr_b16 v[88:89],v3 offset:7168
	ds_read_b64_tr_b16 v[90:91],v3 offset:7680
	s_waitcnt lgkmcnt(0)
	v_mfma_f32_32x32x16_bf16 v[48:63], v[68:71], v[84:87], v[48:63]
	v_mfma_f32_32x32x16_bf16 v[32:47], v[4:7], v[72:75], v[32:47]
	v_mov_b32_e32 v3, v2
	s_nop 1
	v_permlane32_swap_b32_e32 v2, v3
	v_mfma_f32_32x32x16_bf16 v[32:47], v[8:11], v[76:79], v[32:47]
	v_mfma_f32_32x32x16_bf16 v[32:47], v[64:67], v[80:83], v[32:47]
	v_mfma_f32_32x32x16_bf16 v[32:47], v[68:71], v[88:91], v[32:47]
	s_and_saveexec_b64 s[6:7], s[4:5]
	v_add_f32_e32 v2, v2, v3
	ds_write_b32 v239, v2 offset:128
	s_or_b64 exec, exec, s[6:7]
	s_waitcnt lgkmcnt(0)
	ds_read_b128 v[2:5], v234 offset:128
	ds_read_b128 v[6:9], v234 offset:160
	s_lshl_b32 s4, s95, 12
	s_add_i32 s4, s4, 0
	s_add_i32 s4, s4, 0x14800
	s_waitcnt lgkmcnt(1)
	v_rcp_f32_e32 v10, v2
	v_rcp_f32_e32 v11, v3
	v_lshlrev_b32_e32 v68, 9, v238
	v_lshlrev_b32_e32 v69, 1, v237
	v_mul_f32_e32 v48, v48, v10
	v_mul_f32_e32 v10, v32, v10
	v_add3_u32 v68, s4, v68, v69
	v_cvt_pk_bf16_f32 v10, v10, s0
	v_rcp_f32_e32 v12, v4
	ds_write_b16 v68, v10 offset:64
	v_mul_f32_e32 v10, v49, v11
	v_cvt_pk_bf16_f32 v10, v10, s0
	ds_write_b16 v68, v10 offset:128
	v_mul_f32_e32 v10, v33, v11
	v_cvt_pk_bf16_f32 v10, v10, s0
	v_rcp_f32_e32 v13, v5
	ds_write_b16 v68, v10 offset:192
	v_mul_f32_e32 v10, v50, v12
	v_cvt_pk_bf16_f32 v10, v10, s0
	ds_write_b16 v68, v10 offset:256
	v_mul_f32_e32 v10, v34, v12
	v_cvt_pk_bf16_f32 v10, v10, s0
	s_waitcnt lgkmcnt(4)
	v_rcp_f32_e32 v64, v6
	ds_write_b16 v68, v10 offset:320
	v_mul_f32_e32 v10, v51, v13
	v_cvt_pk_bf16_f32 v10, v10, s0
	ds_write_b16 v68, v10 offset:384
	v_mul_f32_e32 v10, v35, v13
	v_cvt_pk_bf16_f32 v10, v10, s0
	v_rcp_f32_e32 v65, v7
	ds_write_b16 v68, v10 offset:448
	v_mul_f32_e32 v10, v52, v64
	v_cvt_pk_bf16_f32 v10, v10, s0
	ds_write_b16 v68, v10 offset:1024
	v_mul_f32_e32 v10, v36, v64
	v_cvt_pk_bf16_f32 v10, v10, s0
	v_rcp_f32_e32 v66, v8
	ds_write_b16 v68, v10 offset:1088
	v_mul_f32_e32 v10, v53, v65
	v_cvt_pk_bf16_f32 v10, v10, s0
	ds_write_b16 v68, v10 offset:1152
	v_mul_f32_e32 v10, v37, v65
	ds_read_b128 v[2:5], v234 offset:192
	v_cvt_pk_bf16_f32 v10, v10, s0
	v_rcp_f32_e32 v67, v9
	ds_write_b16 v68, v10 offset:1216
	v_mul_f32_e32 v10, v54, v66
	v_cvt_pk_bf16_f32 v10, v10, s0
	ds_write_b16 v68, v10 offset:1280
	v_mul_f32_e32 v10, v38, v66
	v_cvt_pk_bf16_f32 v10, v10, s0
	ds_read_b128 v[6:9], v234 offset:224
	s_waitcnt lgkmcnt(3)
	v_rcp_f32_e32 v2, v2
	ds_write_b16 v68, v10 offset:1344
	v_mul_f32_e32 v10, v55, v67
	v_cvt_pk_bf16_f32 v10, v10, s0
	v_rcp_f32_e32 v3, v3
	ds_write_b16 v68, v10 offset:1408
	v_mul_f32_e32 v10, v39, v67
	v_cvt_pk_bf16_f32 v10, v10, s0
	ds_write_b16 v68, v10 offset:1472
	v_mul_f32_e32 v10, v56, v2
	v_mul_f32_e32 v2, v40, v2
	v_cvt_pk_bf16_f32 v2, v2, s0
	v_rcp_f32_e32 v4, v4
	ds_write_b16 v68, v2 offset:2112
	v_mul_f32_e32 v2, v57, v3
	v_cvt_pk_bf16_f32 v2, v2, s0
	ds_write_b16 v68, v2 offset:2176
	v_mul_f32_e32 v2, v41, v3
	v_cvt_pk_bf16_f32 v2, v2, s0
	v_rcp_f32_e32 v5, v5
	ds_write_b16 v68, v2 offset:2240
	v_mul_f32_e32 v2, v58, v4
	v_cvt_pk_bf16_f32 v2, v2, s0
	ds_write_b16 v68, v2 offset:2304
	v_mul_f32_e32 v2, v42, v4
	v_cvt_pk_bf16_f32 v2, v2, s0
	s_waitcnt lgkmcnt(7)
	v_rcp_f32_e32 v6, v6
	ds_write_b16 v68, v2 offset:2368
	v_mul_f32_e32 v2, v59, v5
	v_cvt_pk_bf16_f32 v2, v2, s0
	ds_write_b16 v68, v2 offset:2432
	v_mul_f32_e32 v2, v43, v5
	v_cvt_pk_bf16_f32 v2, v2, s0
	v_rcp_f32_e32 v7, v7
	ds_write_b16 v68, v2 offset:2496
	v_mul_f32_e32 v2, v60, v6
	v_cvt_pk_bf16_f32 v2, v2, s0
	ds_write_b16 v68, v2 offset:3072
	v_mul_f32_e32 v2, v44, v6
	v_cvt_pk_bf16_f32 v2, v2, s0
	v_rcp_f32_e32 v8, v8
	ds_write_b16 v68, v2 offset:3136
	v_mul_f32_e32 v2, v61, v7
	v_cvt_pk_bf16_f32 v2, v2, s0
	ds_write_b16 v68, v2 offset:3200
	v_mul_f32_e32 v2, v45, v7
	v_cvt_pk_bf16_f32 v2, v2, s0
	v_rcp_f32_e32 v9, v9
	ds_write_b16 v68, v2 offset:3264
	v_mul_f32_e32 v2, v62, v8
	v_cvt_pk_bf16_f32 v2, v2, s0
	ds_write_b16 v68, v2 offset:3328
	v_mul_f32_e32 v2, v46, v8
	v_cvt_pk_bf16_f32 v2, v2, s0
	ds_write_b16 v68, v2 offset:3392
	v_mul_f32_e32 v2, v63, v9
	s_waitcnt vmcnt(3)
	v_lshlrev_b32_e32 v12, 16, v140
	v_cvt_pk_bf16_f32 v2, v2, s0
	v_and_b32_e32 v13, 0xffff0000, v140
	v_mul_f32_e32 v4, 0xbfb8aa3b, v12
	ds_write_b16 v68, v2 offset:3456
	v_mul_f32_e32 v2, v47, v9
	v_exp_f32_e32 v8, v4
	v_mul_f32_e32 v4, 0xbfb8aa3b, v13
	v_cvt_pk_bf16_f32 v48, v48, s0
	v_cvt_pk_bf16_f32 v10, v10, s0
	v_cvt_pk_bf16_f32 v2, v2, s0
	v_exp_f32_e32 v9, v4
	ds_write_b16 v68, v48
	ds_write_b16 v68, v10 offset:2048
	ds_write_b16 v68, v2 offset:3520
	v_add_u32_e32 v36, s4, v0
	s_waitcnt lgkmcnt(0)
	v_lshl_add_u64 v[2:3], s[50:51], 0, v[0:1]
	v_lshl_add_u32 v0, v224, 7, v36
	ds_read_b128 v[4:7], v0
	v_add_f32_e32 v0, 1.0, v8
	v_rcp_f32_e32 v32, v0
	v_add_f32_e32 v0, 1.0, v9
	v_rcp_f32_e32 v33, v0
	s_waitcnt lgkmcnt(0)
	v_lshlrev_b32_e32 v34, 16, v4
	v_and_b32_e32 v35, 0xffff0000, v4
	s_bitset1_b32 s8, 10
	v_pk_mul_f32 v[12:13], v[32:33], v[12:13]
	v_lshlrev_b32_e32 v32, 16, v141
	v_and_b32_e32 v33, 0xffff0000, v141
	v_mul_f32_e32 v4, 0xbfb8aa3b, v32
	v_exp_f32_e32 v4, v4
	v_mul_f32_e32 v37, 0xbfb8aa3b, v33
	v_exp_f32_e32 v37, v37
	v_pk_mul_f32 v[12:13], v[12:13], v[34:35]
	v_add_f32_e32 v4, 1.0, v4
	v_rcp_f32_e32 v34, v4
	v_add_f32_e32 v4, 1.0, v37
	v_rcp_f32_e32 v35, v4
	v_cvt_pk_bf16_f32 v4, v12, v13
	v_lshlrev_b32_e32 v12, 16, v5
	v_and_b32_e32 v13, 0xffff0000, v5
	v_pk_mul_f32 v[32:33], v[34:35], v[32:33]
	v_lshlrev_b32_e32 v34, 16, v142
	v_and_b32_e32 v35, 0xffff0000, v142
	v_mul_f32_e32 v5, 0xbfb8aa3b, v34
	v_exp_f32_e32 v5, v5
	v_mul_f32_e32 v37, 0xbfb8aa3b, v35
	v_exp_f32_e32 v37, v37
	v_pk_mul_f32 v[12:13], v[32:33], v[12:13]
	v_add_f32_e32 v5, 1.0, v5
	v_rcp_f32_e32 v32, v5
	v_add_f32_e32 v5, 1.0, v37
	v_rcp_f32_e32 v33, v5
	v_cvt_pk_bf16_f32 v5, v12, v13
	v_lshlrev_b32_e32 v12, 16, v6
	v_and_b32_e32 v13, 0xffff0000, v6
	v_pk_mul_f32 v[32:33], v[32:33], v[34:35]
	v_lshlrev_b32_e32 v34, 16, v143
	v_and_b32_e32 v35, 0xffff0000, v143
	v_mul_f32_e32 v6, 0xbfb8aa3b, v34
	v_exp_f32_e32 v6, v6
	v_mul_f32_e32 v37, 0xbfb8aa3b, v35
	v_exp_f32_e32 v37, v37
	v_pk_mul_f32 v[12:13], v[32:33], v[12:13]
	v_add_f32_e32 v6, 1.0, v6
	v_rcp_f32_e32 v32, v6
	v_add_f32_e32 v6, 1.0, v37
	v_rcp_f32_e32 v33, v6
	v_cvt_pk_bf16_f32 v6, v12, v13
	v_lshlrev_b32_e32 v12, 16, v7
	v_and_b32_e32 v13, 0xffff0000, v7
	v_pk_mul_f32 v[32:33], v[32:33], v[34:35]
	v_or_b32_e32 v0, 8, v224
	v_pk_mul_f32 v[12:13], v[32:33], v[12:13]
	v_lshl_add_u32 v8, v0, 7, v36
	v_cvt_pk_bf16_f32 v7, v12, v13
	v_lshl_add_u64 v[12:13], v[2:3], 0, v[14:15]
	v_lshl_add_u64 v[12:13], v[12:13], 0, s[8:9]
	global_store_dwordx4 v[12:13], v[4:7], off
	ds_read_b128 v[8:11], v8
	s_mov_b64 s[4:5], 0
	s_waitcnt vmcnt(3)
	v_lshlrev_b32_e32 v6, 16, v136
	v_and_b32_e32 v7, 0xffff0000, v136
	v_mul_f32_e32 v4, 0xbfb8aa3b, v6
	v_exp_f32_e32 v5, v4
	v_mul_f32_e32 v4, 0xbfb8aa3b, v7
	v_exp_f32_e32 v13, v4
	v_or_b32_e32 v4, s94, v0
	v_add_f32_e32 v0, 1.0, v5
	v_rcp_f32_e32 v12, v0
	v_add_f32_e32 v0, 1.0, v13
	v_rcp_f32_e32 v13, v0
	s_waitcnt lgkmcnt(0)
	v_lshlrev_b32_e32 v14, 16, v8
	v_and_b32_e32 v15, 0xffff0000, v8
	v_mov_b32_e32 v5, s96
	v_pk_mul_f32 v[6:7], v[12:13], v[6:7]
	v_lshlrev_b32_e32 v12, 16, v137
	v_and_b32_e32 v13, 0xffff0000, v137
	v_mul_f32_e32 v0, 0xbfb8aa3b, v12
	v_exp_f32_e32 v0, v0
	v_mul_f32_e32 v8, 0xbfb8aa3b, v13
	v_exp_f32_e32 v8, v8
	v_pk_mul_f32 v[6:7], v[6:7], v[14:15]
	v_add_f32_e32 v0, 1.0, v0
	v_rcp_f32_e32 v14, v0
	v_add_f32_e32 v0, 1.0, v8
	v_rcp_f32_e32 v15, v0
	v_cvt_pk_bf16_f32 v6, v6, v7
	v_lshlrev_b32_e32 v8, 16, v9
	v_and_b32_e32 v9, 0xffff0000, v9
	v_pk_mul_f32 v[12:13], v[14:15], v[12:13]
	v_lshlrev_b32_e32 v14, 16, v138
	v_and_b32_e32 v15, 0xffff0000, v138
	v_mul_f32_e32 v0, 0xbfb8aa3b, v14
	v_exp_f32_e32 v0, v0
	v_mul_f32_e32 v7, 0xbfb8aa3b, v15
	v_exp_f32_e32 v7, v7
	v_pk_mul_f32 v[8:9], v[12:13], v[8:9]
	v_add_f32_e32 v0, 1.0, v0
	v_rcp_f32_e32 v12, v0
	v_add_f32_e32 v0, 1.0, v7
	v_rcp_f32_e32 v13, v0
	v_cvt_pk_bf16_f32 v7, v8, v9
	v_lshlrev_b32_e32 v8, 16, v10
	v_and_b32_e32 v9, 0xffff0000, v10
	v_pk_mul_f32 v[12:13], v[12:13], v[14:15]
	v_lshlrev_b32_e32 v14, 16, v139
	v_and_b32_e32 v15, 0xffff0000, v139
	v_mul_f32_e32 v0, 0xbfb8aa3b, v14
	v_exp_f32_e32 v0, v0
	v_mul_f32_e32 v10, 0xbfb8aa3b, v15
	v_exp_f32_e32 v10, v10
	v_pk_mul_f32 v[8:9], v[12:13], v[8:9]
	v_add_f32_e32 v0, 1.0, v0
	v_rcp_f32_e32 v12, v0
	v_add_f32_e32 v0, 1.0, v10
	v_rcp_f32_e32 v13, v0
	v_lshlrev_b32_e32 v10, 16, v11
	v_and_b32_e32 v11, 0xffff0000, v11
	v_cvt_pk_bf16_f32 v8, v8, v9
	v_pk_mul_f32 v[12:13], v[12:13], v[14:15]
	v_or_b32_e32 v0, 16, v224
	v_pk_mul_f32 v[10:11], v[12:13], v[10:11]
	s_waitcnt vmcnt(2)
	v_lshlrev_b32_e32 v14, 16, v132
	v_cvt_pk_bf16_f32 v9, v10, v11
	v_lshlrev_b64 v[10:11], 11, v[4:5]
	v_lshl_add_u64 v[10:11], v[2:3], 0, v[10:11]
	v_lshl_add_u64 v[10:11], v[10:11], 0, s[8:9]
	v_lshl_add_u32 v4, v0, 7, v36
	global_store_dwordx4 v[10:11], v[6:9], off
	ds_read_b128 v[6:9], v4
	v_and_b32_e32 v15, 0xffff0000, v132
	v_mul_f32_e32 v4, 0xbfb8aa3b, v14
	v_exp_f32_e32 v10, v4
	v_mul_f32_e32 v4, 0xbfb8aa3b, v15
	v_exp_f32_e32 v11, v4
	v_or_b32_e32 v4, s94, v0
	v_add_f32_e32 v0, 1.0, v10
	v_rcp_f32_e32 v32, v0
	v_add_f32_e32 v0, 1.0, v11
	v_rcp_f32_e32 v33, v0
	v_or_b32_e32 v0, 24, v224
	s_waitcnt lgkmcnt(0)
	v_lshlrev_b32_e32 v34, 16, v6
	v_and_b32_e32 v35, 0xffff0000, v6
	v_pk_mul_f32 v[14:15], v[32:33], v[14:15]
	v_lshlrev_b32_e32 v32, 16, v133
	v_and_b32_e32 v33, 0xffff0000, v133
	v_mul_f32_e32 v6, 0xbfb8aa3b, v32
	v_lshl_add_u32 v10, v0, 7, v36
	v_exp_f32_e32 v6, v6
	v_mul_f32_e32 v36, 0xbfb8aa3b, v33
	v_exp_f32_e32 v36, v36
	v_pk_mul_f32 v[14:15], v[14:15], v[34:35]
	v_add_f32_e32 v6, 1.0, v6
	v_rcp_f32_e32 v34, v6
	v_add_f32_e32 v6, 1.0, v36
	v_rcp_f32_e32 v35, v6
	v_cvt_pk_bf16_f32 v6, v14, v15
	v_lshlrev_b32_e32 v14, 16, v7
	v_and_b32_e32 v15, 0xffff0000, v7
	v_pk_mul_f32 v[32:33], v[34:35], v[32:33]
	v_lshlrev_b32_e32 v34, 16, v134
	v_and_b32_e32 v35, 0xffff0000, v134
	v_mul_f32_e32 v7, 0xbfb8aa3b, v34
	v_exp_f32_e32 v7, v7
	v_mul_f32_e32 v36, 0xbfb8aa3b, v35
	v_exp_f32_e32 v36, v36
	v_pk_mul_f32 v[14:15], v[32:33], v[14:15]
	v_add_f32_e32 v7, 1.0, v7
	v_rcp_f32_e32 v32, v7
	v_add_f32_e32 v7, 1.0, v36
	v_rcp_f32_e32 v33, v7
	v_cvt_pk_bf16_f32 v7, v14, v15
	v_lshlrev_b32_e32 v14, 16, v8
	v_and_b32_e32 v15, 0xffff0000, v8
	v_pk_mul_f32 v[32:33], v[32:33], v[34:35]
	v_lshlrev_b32_e32 v34, 16, v135
	v_and_b32_e32 v35, 0xffff0000, v135
	v_mul_f32_e32 v8, 0xbfb8aa3b, v34
	v_exp_f32_e32 v8, v8
	v_mul_f32_e32 v36, 0xbfb8aa3b, v35
	v_exp_f32_e32 v36, v36
	v_pk_mul_f32 v[14:15], v[32:33], v[14:15]
	v_add_f32_e32 v8, 1.0, v8
	v_rcp_f32_e32 v32, v8
	v_add_f32_e32 v8, 1.0, v36
	v_rcp_f32_e32 v33, v8
	v_cvt_pk_bf16_f32 v8, v14, v15
	v_lshlrev_b32_e32 v14, 16, v9
	v_and_b32_e32 v15, 0xffff0000, v9
	v_pk_mul_f32 v[32:33], v[32:33], v[34:35]
	ds_read_b128 v[10:13], v10
	v_pk_mul_f32 v[14:15], v[32:33], v[14:15]
	s_waitcnt vmcnt(2)
	v_lshlrev_b32_e32 v32, 16, v128
	v_cvt_pk_bf16_f32 v9, v14, v15
	v_lshlrev_b64 v[14:15], 11, v[4:5]
	v_and_b32_e32 v33, 0xffff0000, v128
	v_mul_f32_e32 v4, 0xbfb8aa3b, v32
	v_exp_f32_e32 v4, v4
	v_mul_f32_e32 v34, 0xbfb8aa3b, v33
	v_exp_f32_e32 v34, v34
	v_lshl_add_u64 v[14:15], v[2:3], 0, v[14:15]
	v_lshl_add_u64 v[14:15], v[14:15], 0, s[8:9]
	v_add_f32_e32 v4, 1.0, v4
	global_store_dwordx4 v[14:15], v[6:9], off
	v_lshlrev_b32_e32 v14, 16, v129
	v_and_b32_e32 v15, 0xffff0000, v129
	v_rcp_f32_e32 v6, v4
	v_add_f32_e32 v4, 1.0, v34
	v_rcp_f32_e32 v7, v4
	v_or_b32_e32 v4, s94, v0
	v_mul_f32_e32 v0, 0xbfb8aa3b, v14
	s_waitcnt lgkmcnt(0)
	v_lshlrev_b32_e32 v8, 16, v10
	v_and_b32_e32 v9, 0xffff0000, v10
	v_exp_f32_e32 v0, v0
	v_mul_f32_e32 v10, 0xbfb8aa3b, v15
	v_exp_f32_e32 v10, v10
	v_pk_mul_f32 v[6:7], v[6:7], v[32:33]
	v_add_f32_e32 v0, 1.0, v0
	v_pk_mul_f32 v[6:7], v[6:7], v[8:9]
	v_rcp_f32_e32 v8, v0
	v_add_f32_e32 v0, 1.0, v10
	v_rcp_f32_e32 v9, v0
	v_cvt_pk_bf16_f32 v6, v6, v7
	v_lshlrev_b32_e32 v10, 16, v11
	v_and_b32_e32 v11, 0xffff0000, v11
	v_pk_mul_f32 v[8:9], v[8:9], v[14:15]
	v_lshlrev_b32_e32 v14, 16, v130
	v_and_b32_e32 v15, 0xffff0000, v130
	v_mul_f32_e32 v0, 0xbfb8aa3b, v14
	v_exp_f32_e32 v0, v0
	v_mul_f32_e32 v7, 0xbfb8aa3b, v15
	v_exp_f32_e32 v7, v7
	v_pk_mul_f32 v[8:9], v[8:9], v[10:11]
	v_add_f32_e32 v0, 1.0, v0
	v_rcp_f32_e32 v10, v0
	v_add_f32_e32 v0, 1.0, v7
	v_rcp_f32_e32 v11, v0
	v_cvt_pk_bf16_f32 v7, v8, v9
	v_lshlrev_b32_e32 v8, 16, v12
	v_and_b32_e32 v9, 0xffff0000, v12
	v_pk_mul_f32 v[10:11], v[10:11], v[14:15]
	v_lshlrev_b32_e32 v14, 16, v131
	v_and_b32_e32 v15, 0xffff0000, v131
	v_mul_f32_e32 v0, 0xbfb8aa3b, v14
	v_exp_f32_e32 v0, v0
	v_mul_f32_e32 v12, 0xbfb8aa3b, v15
	v_exp_f32_e32 v12, v12
	v_pk_mul_f32 v[8:9], v[10:11], v[8:9]
	v_add_f32_e32 v0, 1.0, v0
	v_rcp_f32_e32 v10, v0
	v_add_f32_e32 v0, 1.0, v12
	v_rcp_f32_e32 v11, v0
	v_lshlrev_b32_e32 v12, 16, v13
	v_and_b32_e32 v13, 0xffff0000, v13
	v_lshlrev_b64 v[4:5], 11, v[4:5]
	v_pk_mul_f32 v[10:11], v[10:11], v[14:15]
	v_lshl_add_u64 v[2:3], v[2:3], 0, v[4:5]
	v_pk_mul_f32 v[10:11], v[10:11], v[12:13]
	v_cvt_pk_bf16_f32 v8, v8, v9
	v_cvt_pk_bf16_f32 v9, v10, v11
	v_lshl_add_u64 v[2:3], v[2:3], 0, s[8:9]
	global_store_dwordx4 v[2:3], v[6:9], off
	s_waitcnt vmcnt(0) lgkmcnt(0)
	s_barrier

.LBB0_1313:
	s_mov_b32 s6, s47
	s_mov_b32 s7, s46
	v_add_u32_e32 v214, s7, v206
	ds_read_b64_tr_b16 v[210:211], v214 offset:32768
	ds_read_b64_tr_b16 v[212:213], v214 offset:33280
	v_add_f32_e32 v2, v96, v97
	v_add_f32_e32 v2, v98, v2
	v_add_f32_e32 v2, v99, v2
	v_add_f32_e32 v2, v100, v2
	v_add_f32_e32 v2, v101, v2
	v_cvt_pk_bf16_f32 v160, v96, v97
	v_cvt_pk_bf16_f32 v161, v98, v99
	s_waitcnt lgkmcnt(9)
	v_mfma_f32_32x32x16_bf16 v[128:143], v[112:115], v[172:175], v[32:47]
	ds_read_b64_tr_b16 v[96:97], v214 offset:36864
	ds_read_b64_tr_b16 v[98:99], v214 offset:37376
	s_waitcnt lgkmcnt(10)
	v_mfma_f32_32x32x16_bf16 v[112:127], v[188:191], v[172:175], v[32:47]
	v_add_f32_e32 v2, v102, v2
	v_add_f32_e32 v2, v103, v2
	v_add_f32_e32 v2, v104, v2
	v_add_f32_e32 v2, v105, v2
	v_cvt_pk_bf16_f32 v162, v100, v101
	v_cvt_pk_bf16_f32 v163, v102, v103
	ds_read_b64_tr_b16 v[100:101], v214 offset:33792
	ds_read_b64_tr_b16 v[102:103], v214 offset:34304
	v_add_f32_e32 v2, v106, v2
	v_add_f32_e32 v2, v107, v2
	v_add_f32_e32 v2, v108, v2
	v_add_f32_e32 v2, v109, v2
	v_cvt_pk_bf16_f32 v10, v104, v105
	v_cvt_pk_bf16_f32 v11, v106, v107
	s_waitcnt lgkmcnt(11)
	v_mfma_f32_32x32x16_bf16 v[128:143], v[184:187], v[176:179], v[128:143]
	ds_read_b64_tr_b16 v[104:105], v214 offset:37888
	ds_read_b64_tr_b16 v[106:107], v214 offset:38400
	s_waitcnt lgkmcnt(12)
	v_mfma_f32_32x32x16_bf16 v[112:127], v[180:183], v[176:179], v[112:127]
	v_add_f32_e32 v2, v110, v2
	v_add_f32_e32 v2, v111, v2
	v_add_f32_e32 v2, v80, v2
	v_add_f32_e32 v2, v81, v2
	v_cvt_pk_bf16_f32 v12, v108, v109
	v_cvt_pk_bf16_f32 v13, v110, v111
	ds_read_b64_tr_b16 v[108:109], v214 offset:34816
	ds_read_b64_tr_b16 v[110:111], v214 offset:35328
	v_add_f32_e32 v2, v82, v2
	v_add_f32_e32 v2, v83, v2
	v_add_f32_e32 v2, v84, v2
	v_add_f32_e32 v2, v85, v2
	v_cvt_pk_bf16_f32 v6, v80, v81
	v_cvt_pk_bf16_f32 v7, v82, v83
	s_waitcnt lgkmcnt(13)
	v_mfma_f32_32x32x16_bf16 v[128:143], v[156:159], v[168:171], v[128:143]
	ds_read_b64_tr_b16 v[80:81], v214 offset:38912
	ds_read_b64_tr_b16 v[82:83], v214 offset:39424
	s_waitcnt lgkmcnt(14)
	v_mfma_f32_32x32x16_bf16 v[112:127], v[152:155], v[168:171], v[112:127]
	v_add_f32_e32 v2, v86, v2
	v_add_f32_e32 v2, v87, v2
	v_add_f32_e32 v2, v88, v2
	v_add_f32_e32 v2, v89, v2
	v_cvt_pk_bf16_f32 v8, v84, v85
	v_cvt_pk_bf16_f32 v9, v86, v87
	ds_read_b64_tr_b16 v[84:85], v214 offset:35840
	ds_read_b64_tr_b16 v[86:87], v214 offset:36352
	v_add_f32_e32 v2, v90, v2
	v_add_f32_e32 v2, v91, v2
	v_add_f32_e32 v2, v92, v2
	s_waitcnt lgkmcnt(14)
	v_mfma_f32_32x32x16_bf16 v[128:143], v[148:151], v[164:167], v[128:143]
	v_add_f32_e32 v148, v93, v2
	v_cvt_pk_bf16_f32 v2, v88, v89
	v_cvt_pk_bf16_f32 v3, v90, v91
	ds_read_b64_tr_b16 v[88:89], v214 offset:39936
	ds_read_b64_tr_b16 v[90:91], v214 offset:40448
	v_mfma_f32_32x32x16_bf16 v[112:127], v[144:147], v[164:167], v[112:127]
	v_add_f32_e32 v4, v94, v148
	v_add_f32_e32 v144, v95, v4
	v_cvt_pk_bf16_f32 v4, v92, v93
	v_cvt_pk_bf16_f32 v5, v94, v95
	v_lshl_add_u64 v[92:93], v[196:197], 0, s[14:15]
	s_add_i32 s46, s47, s31
	s_mov_b32 s47, m0
	s_mov_b32 m0, s46
	s_nop 0
	global_load_lds_dwordx4 v[92:93], off
	s_mov_b32 m0, s47
	s_add_i32 s46, s45, s42
	s_mov_b32 s47, m0
	s_mov_b32 m0, s46
	s_nop 0
	global_load_lds_dwordx4 v[194:195], off
	s_mov_b32 m0, s47
	v_add_f32_e32 v0, v0, v144
	s_waitcnt lgkmcnt(14)
	v_mfma_f32_32x32x16_bf16 v[48:63], v[160:163], v[210:213], v[48:63]
	v_exp_f32_e32 v128, v128
	v_exp_f32_e32 v129, v129
	v_exp_f32_e32 v130, v130
	v_exp_f32_e32 v131, v131
	s_waitcnt lgkmcnt(12)
	v_mfma_f32_32x32x16_bf16 v[64:79], v[160:163], v[96:99], v[64:79]
	v_exp_f32_e32 v132, v132
	v_exp_f32_e32 v133, v133
	v_exp_f32_e32 v134, v134
	v_exp_f32_e32 v135, v135
	v_add_u32_e32 v96, s44, v208
	ds_read_b128 v[92:95], v96
	ds_read_b128 v[148:151], v96 offset:2048
	v_add_u32_e32 v97, s44, v209
	s_waitcnt lgkmcnt(12)
	v_mfma_f32_32x32x16_bf16 v[48:63], v[10:13], v[100:103], v[48:63]
	v_exp_f32_e32 v136, v136
	v_exp_f32_e32 v137, v137
	v_exp_f32_e32 v138, v138
	v_exp_f32_e32 v139, v139
	ds_read_b128 v[152:155], v97
	ds_read_b128 v[156:159], v97 offset:2048
	s_waitcnt lgkmcnt(12)
	v_mfma_f32_32x32x16_bf16 v[64:79], v[10:13], v[104:107], v[64:79]
	v_exp_f32_e32 v140, v140
	v_exp_f32_e32 v141, v141
	v_exp_f32_e32 v142, v142
	v_exp_f32_e32 v143, v143
	ds_read_b128 v[180:183], v96 offset:4096
	ds_read_b128 v[184:187], v96 offset:6144
	s_waitcnt lgkmcnt(12)
	v_mfma_f32_32x32x16_bf16 v[48:63], v[6:9], v[108:111], v[48:63]
	v_exp_f32_e32 v112, v112
	v_exp_f32_e32 v113, v113
	v_exp_f32_e32 v114, v114
	v_exp_f32_e32 v115, v115
	ds_read_b128 v[188:191], v97 offset:4096
	ds_read_b128 v[144:147], v97 offset:6144
	s_waitcnt lgkmcnt(12)
	v_mfma_f32_32x32x16_bf16 v[64:79], v[6:9], v[80:83], v[64:79]
	v_exp_f32_e32 v116, v116
	v_exp_f32_e32 v117, v117
	v_exp_f32_e32 v118, v118
	v_exp_f32_e32 v119, v119
	s_waitcnt lgkmcnt(10)
	v_mfma_f32_32x32x16_bf16 v[48:63], v[2:5], v[84:87], v[48:63]
	v_exp_f32_e32 v120, v120
	v_exp_f32_e32 v121, v121
	v_exp_f32_e32 v122, v122
	v_exp_f32_e32 v123, v123
	s_waitcnt lgkmcnt(8)
	v_mfma_f32_32x32x16_bf16 v[64:79], v[2:5], v[88:91], v[64:79]
	v_exp_f32_e32 v124, v124
	v_exp_f32_e32 v125, v125
	v_exp_f32_e32 v126, v126
	v_exp_f32_e32 v127, v127
	s_waitcnt vmcnt(4) lgkmcnt(0)
	s_barrier
	v_add_u32_e32 v218, s6, v206
	ds_read_b64_tr_b16 v[210:211], v218 offset:32768
	ds_read_b64_tr_b16 v[212:213], v218 offset:33280
	s_waitcnt lgkmcnt(9)
	v_mfma_f32_32x32x16_bf16 v[96:111], v[92:95], v[172:175], v[32:47]
	v_add_f32_e32 v2, v128, v129
	v_add_f32_e32 v2, v130, v2
	v_add_f32_e32 v2, v131, v2
	v_add_f32_e32 v2, v132, v2
	v_add_f32_e32 v2, v133, v2
	v_cvt_pk_bf16_f32 v160, v128, v129
	v_cvt_pk_bf16_f32 v161, v130, v131
	ds_read_b64_tr_b16 v[128:129], v218 offset:36864
	ds_read_b64_tr_b16 v[130:131], v218 offset:37376
	s_waitcnt lgkmcnt(10)
	v_mfma_f32_32x32x16_bf16 v[80:95], v[148:151], v[172:175], v[32:47]
	v_add_f32_e32 v2, v134, v2
	v_add_f32_e32 v2, v135, v2
	v_add_f32_e32 v2, v136, v2
	v_add_f32_e32 v2, v137, v2
	v_cvt_pk_bf16_f32 v162, v132, v133
	v_cvt_pk_bf16_f32 v163, v134, v135
	ds_read_b64_tr_b16 v[132:133], v218 offset:33792
	ds_read_b64_tr_b16 v[134:135], v218 offset:34304
	s_waitcnt lgkmcnt(11)
	v_mfma_f32_32x32x16_bf16 v[96:111], v[152:155], v[176:179], v[96:111]
	v_add_f32_e32 v2, v138, v2
	v_add_f32_e32 v2, v139, v2
	v_add_f32_e32 v2, v140, v2
	v_add_f32_e32 v2, v141, v2
	v_cvt_pk_bf16_f32 v10, v136, v137
	v_cvt_pk_bf16_f32 v11, v138, v139
	ds_read_b64_tr_b16 v[136:137], v218 offset:37888
	ds_read_b64_tr_b16 v[138:139], v218 offset:38400
	s_waitcnt lgkmcnt(12)
	v_mfma_f32_32x32x16_bf16 v[80:95], v[156:159], v[176:179], v[80:95]
	v_add_f32_e32 v2, v142, v2
	v_add_f32_e32 v2, v143, v2
	v_add_f32_e32 v2, v112, v2
	v_add_f32_e32 v2, v113, v2
	v_cvt_pk_bf16_f32 v12, v140, v141
	v_cvt_pk_bf16_f32 v13, v142, v143
	ds_read_b64_tr_b16 v[140:141], v218 offset:34816
	ds_read_b64_tr_b16 v[142:143], v218 offset:35328
	s_waitcnt lgkmcnt(13)
	v_mfma_f32_32x32x16_bf16 v[96:111], v[180:183], v[168:171], v[96:111]
	v_add_f32_e32 v2, v114, v2
	v_add_f32_e32 v2, v115, v2
	v_add_f32_e32 v2, v116, v2
	v_add_f32_e32 v2, v117, v2
	v_cvt_pk_bf16_f32 v6, v112, v113
	v_cvt_pk_bf16_f32 v7, v114, v115
	ds_read_b64_tr_b16 v[214:215], v218 offset:38912
	ds_read_b64_tr_b16 v[216:217], v218 offset:39424
	s_waitcnt lgkmcnt(14)
	v_mfma_f32_32x32x16_bf16 v[80:95], v[184:187], v[168:171], v[80:95]
	v_add_f32_e32 v2, v118, v2
	v_add_f32_e32 v2, v119, v2
	v_add_f32_e32 v2, v120, v2
	v_add_f32_e32 v2, v121, v2
	v_cvt_pk_bf16_f32 v8, v116, v117
	v_cvt_pk_bf16_f32 v9, v118, v119
	ds_read_b64_tr_b16 v[116:117], v218 offset:35840
	ds_read_b64_tr_b16 v[118:119], v218 offset:36352
	s_waitcnt lgkmcnt(14)
	v_mfma_f32_32x32x16_bf16 v[96:111], v[188:191], v[164:167], v[96:111]
	v_add_f32_e32 v2, v122, v2
	v_add_f32_e32 v2, v123, v2
	v_add_f32_e32 v2, v124, v2
	v_add_f32_e32 v112, v125, v2
	v_cvt_pk_bf16_f32 v2, v120, v121
	v_cvt_pk_bf16_f32 v3, v122, v123
	ds_read_b64_tr_b16 v[120:121], v218 offset:39936
	ds_read_b64_tr_b16 v[122:123], v218 offset:40448
	v_mfma_f32_32x32x16_bf16 v[80:95], v[144:147], v[164:167], v[80:95]
	v_add_f32_e32 v4, v126, v112
	v_add_f32_e32 v112, v127, v4
	v_cvt_pk_bf16_f32 v4, v124, v125
	v_cvt_pk_bf16_f32 v5, v126, v127
	s_nop 0
	v_add_f32_e32 v0, v0, v112
	v_lshl_add_u64 v[112:113], v[196:197], 0, s[40:41]
	s_add_i32 s46, s44, s31
	s_mov_b32 s47, m0
	s_mov_b32 m0, s46
	s_nop 0
	global_load_lds_dwordx4 v[112:113], off
	s_mov_b32 m0, s47
	v_lshl_add_u64 v[112:113], v[198:199], 0, s[24:25]
	s_add_i32 s46, s7, s42
	s_mov_b32 s47, m0
	s_mov_b32 m0, s46
	s_nop 0
	global_load_lds_dwordx4 v[112:113], off
	s_mov_b32 m0, s47
	s_waitcnt lgkmcnt(14)
	v_mfma_f32_32x32x16_bf16 v[48:63], v[160:163], v[210:213], v[48:63]
	v_exp_f32_e32 v96, v96
	v_exp_f32_e32 v97, v97
	v_exp_f32_e32 v98, v98
	v_exp_f32_e32 v99, v99
	s_waitcnt lgkmcnt(12)
	v_mfma_f32_32x32x16_bf16 v[64:79], v[160:163], v[128:131], v[64:79]
	v_exp_f32_e32 v100, v100
	v_exp_f32_e32 v101, v101
	v_exp_f32_e32 v102, v102
	v_exp_f32_e32 v103, v103
	v_add_u32_e32 v124, s45, v208
	ds_read_b128 v[112:115], v124
	ds_read_b128 v[188:191], v124 offset:2048
	v_add_u32_e32 v125, s45, v209
	s_waitcnt lgkmcnt(12)
	v_mfma_f32_32x32x16_bf16 v[48:63], v[10:13], v[132:135], v[48:63]
	v_exp_f32_e32 v104, v104
	v_exp_f32_e32 v105, v105
	v_exp_f32_e32 v106, v106
	v_exp_f32_e32 v107, v107
	ds_read_b128 v[184:187], v125
	ds_read_b128 v[180:183], v125 offset:2048
	s_waitcnt lgkmcnt(12)
	v_mfma_f32_32x32x16_bf16 v[64:79], v[10:13], v[136:139], v[64:79]
	v_exp_f32_e32 v108, v108
	v_exp_f32_e32 v109, v109
	v_exp_f32_e32 v110, v110
	v_exp_f32_e32 v111, v111
	ds_read_b128 v[156:159], v124 offset:4096
	ds_read_b128 v[152:155], v124 offset:6144
	s_waitcnt lgkmcnt(12)
	v_mfma_f32_32x32x16_bf16 v[48:63], v[6:9], v[140:143], v[48:63]
	v_exp_f32_e32 v80, v80
	v_exp_f32_e32 v81, v81
	v_exp_f32_e32 v82, v82
	v_exp_f32_e32 v83, v83
	ds_read_b128 v[148:151], v125 offset:4096
	ds_read_b128 v[144:147], v125 offset:6144
	s_waitcnt lgkmcnt(12)
	v_mfma_f32_32x32x16_bf16 v[64:79], v[6:9], v[214:217], v[64:79]
	v_exp_f32_e32 v84, v84
	v_exp_f32_e32 v85, v85
	v_exp_f32_e32 v86, v86
	v_exp_f32_e32 v87, v87
	s_waitcnt lgkmcnt(10)
	v_mfma_f32_32x32x16_bf16 v[48:63], v[2:5], v[116:119], v[48:63]
	v_exp_f32_e32 v88, v88
	v_exp_f32_e32 v89, v89
	v_exp_f32_e32 v90, v90
	v_exp_f32_e32 v91, v91
	s_waitcnt lgkmcnt(8)
	v_mfma_f32_32x32x16_bf16 v[64:79], v[2:5], v[120:123], v[64:79]
	v_exp_f32_e32 v92, v92
	v_exp_f32_e32 v93, v93
	v_exp_f32_e32 v94, v94
	v_exp_f32_e32 v95, v95
	s_waitcnt vmcnt(4) lgkmcnt(0)
	s_barrier
	s_add_i32 s43, s43, 2
	v_lshl_add_u64 v[194:195], v[194:195], 0, s[22:23]
	v_lshl_add_u64 v[196:197], v[196:197], 0, s[22:23]
	v_lshl_add_u64 v[198:199], v[198:199], 0, s[22:23]
	s_mov_b32 s46, s44
	s_mov_b32 s47, s45
	s_mov_b32 s44, s7
	s_cmp_gt_u32 s43, 60
	s_mov_b32 s45, s6
	s_cbranch_scc0 .LBB0_1313
	s_and_b32 s6, s21, 0x3fffffc0
	s_lshl_b32 s6, s6, 2
	s_add_i32 s31, s6, 0
	s_add_i32 s31, s31, 0x10000
	ds_read_b64_tr_b16 v[194:195], v206 offset:49152
	ds_read_b64_tr_b16 v[196:197], v206 offset:49664
	s_waitcnt lgkmcnt(9)
	v_mfma_f32_32x32x16_bf16 v[128:143], v[112:115], v[172:175], v[32:47]
	v_add_f32_e32 v2, v96, v97
	v_add_f32_e32 v2, v98, v2
	v_add_f32_e32 v2, v99, v2
	v_add_f32_e32 v2, v100, v2
	v_add_f32_e32 v2, v101, v2
	v_cvt_pk_bf16_f32 v160, v96, v97
	v_cvt_pk_bf16_f32 v161, v98, v99
	ds_read_b64_tr_b16 v[96:97], v206 offset:53248
	ds_read_b64_tr_b16 v[98:99], v206 offset:53760
	v_add_f32_e32 v2, v102, v2
	v_add_f32_e32 v2, v103, v2
	v_add_f32_e32 v2, v104, v2
	v_add_f32_e32 v2, v105, v2
	v_cvt_pk_bf16_f32 v162, v100, v101
	v_cvt_pk_bf16_f32 v163, v102, v103
	s_waitcnt lgkmcnt(10)
	v_mfma_f32_32x32x16_bf16 v[112:127], v[188:191], v[172:175], v[32:47]
	ds_read_b64_tr_b16 v[100:101], v206 offset:50176
	ds_read_b64_tr_b16 v[102:103], v206 offset:50688
	s_waitcnt lgkmcnt(11)
	v_mfma_f32_32x32x16_bf16 v[128:143], v[184:187], v[176:179], v[128:143]
	v_add_f32_e32 v2, v106, v2
	v_add_f32_e32 v2, v107, v2
	v_add_f32_e32 v2, v108, v2
	v_add_f32_e32 v2, v109, v2
	v_cvt_pk_bf16_f32 v10, v104, v105
	v_cvt_pk_bf16_f32 v11, v106, v107
	ds_read_b64_tr_b16 v[104:105], v206 offset:54272
	ds_read_b64_tr_b16 v[106:107], v206 offset:54784
	v_add_f32_e32 v2, v110, v2
	v_add_f32_e32 v2, v111, v2
	v_add_f32_e32 v2, v80, v2
	v_add_f32_e32 v2, v81, v2
	v_cvt_pk_bf16_f32 v12, v108, v109
	v_cvt_pk_bf16_f32 v13, v110, v111
	s_waitcnt lgkmcnt(12)
	v_mfma_f32_32x32x16_bf16 v[112:127], v[180:183], v[176:179], v[112:127]
	ds_read_b64_tr_b16 v[108:109], v206 offset:51200
	ds_read_b64_tr_b16 v[110:111], v206 offset:51712
	s_waitcnt lgkmcnt(13)
	v_mfma_f32_32x32x16_bf16 v[128:143], v[156:159], v[168:171], v[128:143]
	v_add_f32_e32 v2, v82, v2
	v_add_f32_e32 v2, v83, v2
	v_add_f32_e32 v2, v84, v2
	v_add_f32_e32 v2, v85, v2
	v_cvt_pk_bf16_f32 v6, v80, v81
	v_cvt_pk_bf16_f32 v7, v82, v83
	ds_read_b64_tr_b16 v[80:81], v206 offset:55296
	ds_read_b64_tr_b16 v[82:83], v206 offset:55808
	v_add_f32_e32 v2, v86, v2
	v_add_f32_e32 v2, v87, v2
	v_add_f32_e32 v2, v88, v2
	v_add_f32_e32 v2, v89, v2
	v_cvt_pk_bf16_f32 v8, v84, v85
	v_cvt_pk_bf16_f32 v9, v86, v87
	s_waitcnt lgkmcnt(14)
	v_mfma_f32_32x32x16_bf16 v[112:127], v[152:155], v[168:171], v[112:127]
	ds_read_b64_tr_b16 v[84:85], v206 offset:52224
	ds_read_b64_tr_b16 v[86:87], v206 offset:52736
	s_waitcnt lgkmcnt(14)
	v_mfma_f32_32x32x16_bf16 v[128:143], v[148:151], v[164:167], v[128:143]
	v_add_f32_e32 v2, v90, v2
	v_add_f32_e32 v2, v91, v2
	v_add_f32_e32 v2, v92, v2
	v_add_f32_e32 v152, v93, v2
	v_cvt_pk_bf16_f32 v2, v88, v89
	v_cvt_pk_bf16_f32 v3, v90, v91
	ds_read_b64_tr_b16 v[88:89], v206 offset:56320
	ds_read_b64_tr_b16 v[90:91], v206 offset:56832
	v_add_f32_e32 v4, v94, v152
	v_add_f32_e32 v148, v95, v4
	v_cvt_pk_bf16_f32 v4, v92, v93
	v_cvt_pk_bf16_f32 v5, v94, v95
	v_mfma_f32_32x32x16_bf16 v[112:127], v[144:147], v[164:167], v[112:127]
	s_mov_b64 s[42:43], 0x10c000
	v_lshl_add_u64 v[92:93], v[192:193], 0, s[42:43]
	s_mov_b32 s6, m0
	s_mov_b32 m0, s20
	s_nop 0
	global_load_lds_dwordx4 v[92:93], off
	s_mov_b32 m0, s6
	s_mov_b64 s[6:7], 0x104000
	s_cmp_lg_u32 0, -1
	v_lshl_add_u64 v[92:93], v[14:15], 0, s[6:7]
	s_cselect_b32 s6, 0, 0
	s_add_i32 s7, s6, s8
	s_add_i32 s20, s7, 0xa000
	s_mov_b32 s21, m0
	s_mov_b32 m0, s20
	s_nop 0
	global_load_lds_dwordx4 v[92:93], off
	s_mov_b32 m0, s21
	v_add_f32_e32 v0, v0, v148
	s_waitcnt lgkmcnt(14)
	v_mfma_f32_32x32x16_bf16 v[48:63], v[160:163], v[194:197], v[48:63]
	v_exp_f32_e32 v128, v128
	v_exp_f32_e32 v129, v129
	v_exp_f32_e32 v130, v130
	v_exp_f32_e32 v131, v131
	s_waitcnt lgkmcnt(12)
	v_mfma_f32_32x32x16_bf16 v[64:79], v[160:163], v[96:99], v[64:79]
	v_exp_f32_e32 v132, v132
	v_exp_f32_e32 v133, v133
	v_exp_f32_e32 v134, v134
	v_exp_f32_e32 v135, v135
	ds_read_b128 v[92:95], v208
	ds_read_b128 v[180:183], v208 offset:2048
	s_waitcnt lgkmcnt(12)
	v_mfma_f32_32x32x16_bf16 v[48:63], v[10:13], v[100:103], v[48:63]
	v_exp_f32_e32 v136, v136
	v_exp_f32_e32 v137, v137
	v_exp_f32_e32 v138, v138
	v_exp_f32_e32 v139, v139
	ds_read_b128 v[100:103], v209
	ds_read_b128 v[184:187], v209 offset:2048
	s_waitcnt lgkmcnt(12)
	v_mfma_f32_32x32x16_bf16 v[64:79], v[10:13], v[104:107], v[64:79]
	v_exp_f32_e32 v140, v140
	v_exp_f32_e32 v141, v141
	v_exp_f32_e32 v142, v142
	v_exp_f32_e32 v143, v143
	ds_read_b128 v[104:107], v208 offset:4096
	ds_read_b128 v[188:191], v208 offset:6144
	s_waitcnt lgkmcnt(12)
	v_mfma_f32_32x32x16_bf16 v[48:63], v[6:9], v[108:111], v[48:63]
	v_exp_f32_e32 v112, v112
	v_exp_f32_e32 v113, v113
	v_exp_f32_e32 v114, v114
	v_exp_f32_e32 v115, v115
	ds_read_b128 v[108:111], v209 offset:4096
	ds_read_b128 v[96:99], v209 offset:6144
	s_waitcnt lgkmcnt(12)
	v_mfma_f32_32x32x16_bf16 v[64:79], v[6:9], v[80:83], v[64:79]
	v_exp_f32_e32 v116, v116
	v_exp_f32_e32 v117, v117
	v_exp_f32_e32 v118, v118
	v_exp_f32_e32 v119, v119
	s_waitcnt lgkmcnt(10)
	v_mfma_f32_32x32x16_bf16 v[48:63], v[2:5], v[84:87], v[48:63]
	v_exp_f32_e32 v120, v120
	v_exp_f32_e32 v121, v121
	v_exp_f32_e32 v122, v122
	v_exp_f32_e32 v123, v123
	s_waitcnt lgkmcnt(8)
	v_mfma_f32_32x32x16_bf16 v[64:79], v[2:5], v[88:91], v[64:79]
	v_exp_f32_e32 v124, v124
	v_exp_f32_e32 v125, v125
	v_exp_f32_e32 v126, v126
	v_exp_f32_e32 v127, v127
	s_waitcnt vmcnt(4) lgkmcnt(0)
	s_barrier
	ds_read_b64_tr_b16 v[192:193], v206 offset:57344
	ds_read_b64_tr_b16 v[194:195], v206 offset:57856
	v_add_f32_e32 v2, v128, v129
	v_add_f32_e32 v2, v130, v2
	v_add_f32_e32 v2, v131, v2
	v_add_f32_e32 v2, v132, v2
	v_add_f32_e32 v2, v133, v2
	v_cvt_pk_bf16_f32 v160, v128, v129
	v_cvt_pk_bf16_f32 v161, v130, v131
	s_waitcnt lgkmcnt(9)
	v_mfma_f32_32x32x16_bf16 v[144:159], v[92:95], v[172:175], v[32:47]
	ds_read_b64_tr_b16 v[128:129], v206 offset:61440
	ds_read_b64_tr_b16 v[130:131], v206 offset:61952
	s_waitcnt lgkmcnt(10)
	v_mfma_f32_32x32x16_bf16 v[80:95], v[180:183], v[172:175], v[32:47]
	v_add_f32_e32 v2, v134, v2
	v_add_f32_e32 v2, v135, v2
	v_add_f32_e32 v2, v136, v2
	v_add_f32_e32 v2, v137, v2
	v_cvt_pk_bf16_f32 v162, v132, v133
	v_cvt_pk_bf16_f32 v163, v134, v135
	ds_read_b64_tr_b16 v[132:133], v206 offset:58368
	ds_read_b64_tr_b16 v[134:135], v206 offset:58880
	v_add_f32_e32 v2, v138, v2
	v_add_f32_e32 v2, v139, v2
	v_add_f32_e32 v2, v140, v2
	v_add_f32_e32 v2, v141, v2
	v_cvt_pk_bf16_f32 v10, v136, v137
	v_cvt_pk_bf16_f32 v11, v138, v139
	s_waitcnt lgkmcnt(11)
	v_mfma_f32_32x32x16_bf16 v[144:159], v[100:103], v[176:179], v[144:159]
	ds_read_b64_tr_b16 v[100:101], v206 offset:62464
	ds_read_b64_tr_b16 v[102:103], v206 offset:62976
	s_waitcnt lgkmcnt(12)
	v_mfma_f32_32x32x16_bf16 v[80:95], v[184:187], v[176:179], v[80:95]
	v_add_f32_e32 v2, v142, v2
	v_add_f32_e32 v2, v143, v2
	v_add_f32_e32 v2, v112, v2
	v_add_f32_e32 v2, v113, v2
	v_cvt_pk_bf16_f32 v12, v140, v141
	v_cvt_pk_bf16_f32 v13, v142, v143
	ds_read_b64_tr_b16 v[136:137], v206 offset:59392
	ds_read_b64_tr_b16 v[138:139], v206 offset:59904
	v_add_f32_e32 v2, v114, v2
	v_add_f32_e32 v2, v115, v2
	v_add_f32_e32 v2, v116, v2
	v_add_f32_e32 v2, v117, v2
	v_cvt_pk_bf16_f32 v6, v112, v113
	v_cvt_pk_bf16_f32 v7, v114, v115
	s_waitcnt lgkmcnt(13)
	v_mfma_f32_32x32x16_bf16 v[144:159], v[104:107], v[168:171], v[144:159]
	ds_read_b64_tr_b16 v[104:105], v206 offset:63488
	ds_read_b64_tr_b16 v[106:107], v206 offset:64000
	s_waitcnt lgkmcnt(14)
	v_mfma_f32_32x32x16_bf16 v[80:95], v[188:191], v[168:171], v[80:95]
	v_add_f32_e32 v2, v118, v2
	v_add_f32_e32 v2, v119, v2
	v_add_f32_e32 v2, v120, v2
	v_add_f32_e32 v2, v121, v2
	v_cvt_pk_bf16_f32 v8, v116, v117
	v_cvt_pk_bf16_f32 v9, v118, v119
	ds_read_b64_tr_b16 v[116:117], v206 offset:60416
	ds_read_b64_tr_b16 v[118:119], v206 offset:60928
	v_add_f32_e32 v2, v122, v2
	v_add_f32_e32 v2, v123, v2
	v_add_f32_e32 v2, v124, v2
	v_add_f32_e32 v112, v125, v2
	v_cvt_pk_bf16_f32 v2, v120, v121
	v_cvt_pk_bf16_f32 v3, v122, v123
	s_waitcnt lgkmcnt(14)
	v_mfma_f32_32x32x16_bf16 v[144:159], v[108:111], v[164:167], v[144:159]
	ds_read_b64_tr_b16 v[108:109], v206 offset:64512
	ds_read_b64_tr_b16 v[110:111], v206 offset:65024
	v_mfma_f32_32x32x16_bf16 v[80:95], v[96:99], v[164:167], v[80:95]
	v_add_f32_e32 v4, v126, v112
	v_add_f32_e32 v96, v127, v4
	v_cvt_pk_bf16_f32 v4, v124, v125
	v_cvt_pk_bf16_f32 v5, v126, v127
	s_mov_b64 s[20:21], 0x108000
	v_add_f32_e32 v0, v0, v96
	v_lshl_add_u64 v[96:97], v[14:15], 0, s[20:21]
	s_add_i32 s7, s7, 0xc000
	s_mov_b32 s20, m0
	s_mov_b32 m0, s7
	s_nop 0
	global_load_lds_dwordx4 v[96:97], off
	s_mov_b32 m0, s20
	s_waitcnt lgkmcnt(14)
	v_mfma_f32_32x32x16_bf16 v[48:63], v[160:163], v[192:195], v[48:63]
	v_exp_f32_e32 v144, v144
	v_exp_f32_e32 v145, v145
	v_exp_f32_e32 v146, v146
	v_exp_f32_e32 v147, v147
	s_waitcnt lgkmcnt(12)
	v_mfma_f32_32x32x16_bf16 v[64:79], v[160:163], v[128:131], v[64:79]
	v_exp_f32_e32 v148, v148
	v_exp_f32_e32 v149, v149
	v_exp_f32_e32 v150, v150
	v_exp_f32_e32 v151, v151
	ds_read_b128 v[96:99], v208 offset:8192
	ds_read_b128 v[120:123], v208 offset:10240
	s_waitcnt lgkmcnt(12)
	v_mfma_f32_32x32x16_bf16 v[48:63], v[10:13], v[132:135], v[48:63]
	v_exp_f32_e32 v152, v152
	v_exp_f32_e32 v153, v153
	v_exp_f32_e32 v154, v154
	v_exp_f32_e32 v155, v155
	ds_read_b128 v[124:127], v209 offset:8192
	ds_read_b128 v[180:183], v209 offset:10240
	s_waitcnt lgkmcnt(12)
	v_mfma_f32_32x32x16_bf16 v[64:79], v[10:13], v[100:103], v[64:79]
	v_exp_f32_e32 v156, v156
	v_exp_f32_e32 v157, v157
	v_exp_f32_e32 v158, v158
	v_exp_f32_e32 v159, v159
	ds_read_b128 v[184:187], v208 offset:12288
	ds_read_b128 v[188:191], v208 offset:14336
	s_waitcnt lgkmcnt(12)
	v_mfma_f32_32x32x16_bf16 v[48:63], v[6:9], v[136:139], v[48:63]
	v_exp_f32_e32 v80, v80
	v_exp_f32_e32 v81, v81
	v_exp_f32_e32 v82, v82
	v_exp_f32_e32 v83, v83
	ds_read_b128 v[192:195], v209 offset:12288
	ds_read_b128 v[112:115], v209 offset:14336
	s_waitcnt lgkmcnt(12)
	v_mfma_f32_32x32x16_bf16 v[64:79], v[6:9], v[104:107], v[64:79]
	v_exp_f32_e32 v84, v84
	v_exp_f32_e32 v85, v85
	v_exp_f32_e32 v86, v86
	v_exp_f32_e32 v87, v87
	s_waitcnt lgkmcnt(10)
	v_mfma_f32_32x32x16_bf16 v[48:63], v[2:5], v[116:119], v[48:63]
	v_exp_f32_e32 v88, v88
	v_exp_f32_e32 v89, v89
	v_exp_f32_e32 v90, v90
	v_exp_f32_e32 v91, v91
	s_waitcnt lgkmcnt(8)
	v_mfma_f32_32x32x16_bf16 v[64:79], v[2:5], v[108:111], v[64:79]
	v_exp_f32_e32 v92, v92
	v_exp_f32_e32 v93, v93
	v_exp_f32_e32 v94, v94
	v_exp_f32_e32 v95, v95
	s_waitcnt vmcnt(3) lgkmcnt(0)
	s_barrier
	ds_read_b64_tr_b16 v[116:117], v206 offset:32768
	ds_read_b64_tr_b16 v[118:119], v206 offset:33280
	s_waitcnt lgkmcnt(9)
	v_mfma_f32_32x32x16_bf16 v[128:143], v[96:99], v[172:175], v[32:47]
	v_add_f32_e32 v2, v144, v145
	v_add_f32_e32 v2, v146, v2
	v_add_f32_e32 v2, v147, v2
	v_add_f32_e32 v2, v148, v2
	v_add_f32_e32 v2, v149, v2
	v_cvt_pk_bf16_f32 v160, v144, v145
	v_cvt_pk_bf16_f32 v161, v146, v147
	ds_read_b64_tr_b16 v[144:145], v206 offset:36864
	ds_read_b64_tr_b16 v[146:147], v206 offset:37376
	v_add_f32_e32 v2, v150, v2
	v_add_f32_e32 v2, v151, v2
	v_add_f32_e32 v2, v152, v2
	v_add_f32_e32 v2, v153, v2
	v_cvt_pk_bf16_f32 v162, v148, v149
	v_cvt_pk_bf16_f32 v163, v150, v151
	s_waitcnt lgkmcnt(10)
	v_mfma_f32_32x32x16_bf16 v[96:111], v[120:123], v[172:175], v[32:47]
	ds_read_b64_tr_b16 v[120:121], v206 offset:33792
	ds_read_b64_tr_b16 v[122:123], v206 offset:34304
	s_waitcnt lgkmcnt(11)
	v_mfma_f32_32x32x16_bf16 v[128:143], v[124:127], v[176:179], v[128:143]
	v_add_f32_e32 v2, v154, v2
	v_add_f32_e32 v2, v155, v2
	v_add_f32_e32 v2, v156, v2
	v_add_f32_e32 v2, v157, v2
	v_cvt_pk_bf16_f32 v10, v152, v153
	v_cvt_pk_bf16_f32 v11, v154, v155
	ds_read_b64_tr_b16 v[124:125], v206 offset:37888
	ds_read_b64_tr_b16 v[126:127], v206 offset:38400
	v_add_f32_e32 v2, v158, v2
	v_add_f32_e32 v2, v159, v2
	v_add_f32_e32 v2, v80, v2
	v_add_f32_e32 v2, v81, v2
	v_cvt_pk_bf16_f32 v12, v156, v157
	v_cvt_pk_bf16_f32 v13, v158, v159
	s_waitcnt lgkmcnt(12)
	v_mfma_f32_32x32x16_bf16 v[96:111], v[180:183], v[176:179], v[96:111]
	ds_read_b64_tr_b16 v[148:149], v206 offset:34816
	ds_read_b64_tr_b16 v[150:151], v206 offset:35328
	s_waitcnt lgkmcnt(13)
	v_mfma_f32_32x32x16_bf16 v[128:143], v[184:187], v[168:171], v[128:143]
	v_add_f32_e32 v2, v82, v2
	v_add_f32_e32 v2, v83, v2
	v_add_f32_e32 v2, v84, v2
	v_add_f32_e32 v2, v85, v2
	v_cvt_pk_bf16_f32 v6, v80, v81
	v_cvt_pk_bf16_f32 v7, v82, v83
	ds_read_b64_tr_b16 v[80:81], v206 offset:38912
	ds_read_b64_tr_b16 v[82:83], v206 offset:39424
	v_add_f32_e32 v2, v86, v2
	v_add_f32_e32 v2, v87, v2
	v_add_f32_e32 v2, v88, v2
	v_add_f32_e32 v2, v89, v2
	v_cvt_pk_bf16_f32 v8, v84, v85
	v_cvt_pk_bf16_f32 v9, v86, v87
	s_waitcnt lgkmcnt(14)
	v_mfma_f32_32x32x16_bf16 v[96:111], v[188:191], v[168:171], v[96:111]
	ds_read_b64_tr_b16 v[84:85], v206 offset:35840
	ds_read_b64_tr_b16 v[86:87], v206 offset:36352
	s_waitcnt lgkmcnt(14)
	v_mfma_f32_32x32x16_bf16 v[128:143], v[192:195], v[164:167], v[128:143]
	v_add_f32_e32 v2, v90, v2
	v_add_f32_e32 v2, v91, v2
	v_add_f32_e32 v2, v92, v2
	v_add_f32_e32 v152, v93, v2
	v_cvt_pk_bf16_f32 v2, v88, v89
	v_cvt_pk_bf16_f32 v3, v90, v91
	ds_read_b64_tr_b16 v[88:89], v206 offset:39936
	ds_read_b64_tr_b16 v[90:91], v206 offset:40448
	v_add_f32_e32 v4, v94, v152
	v_add_f32_e32 v152, v95, v4
	v_cvt_pk_bf16_f32 v4, v92, v93
	v_cvt_pk_bf16_f32 v5, v94, v95
	v_mfma_f32_32x32x16_bf16 v[96:111], v[112:115], v[164:167], v[96:111]
	s_add_i32 s6, s6, 0xe000
	v_lshl_add_u64 v[14:15], v[14:15], 0, s[42:43]
	s_add_i32 s8, s8, s6
	s_mov_b32 s7, m0
	s_mov_b32 m0, s8
	s_nop 0
	global_load_lds_dwordx4 v[14:15], off
	s_mov_b32 m0, s7
	v_add_f32_e32 v0, v0, v152
	s_mov_b64 s[80:81], 0x10c000
	s_waitcnt lgkmcnt(14)
	v_mfma_f32_32x32x16_bf16 v[48:63], v[160:163], v[116:119], v[48:63]
	v_exp_f32_e32 v128, v128
	v_exp_f32_e32 v129, v129
	v_exp_f32_e32 v130, v130
	v_exp_f32_e32 v131, v131
	s_waitcnt lgkmcnt(12)
	v_mfma_f32_32x32x16_bf16 v[64:79], v[160:163], v[144:147], v[64:79]
	v_exp_f32_e32 v132, v132
	v_exp_f32_e32 v133, v133
	v_exp_f32_e32 v134, v134
	v_exp_f32_e32 v135, v135
	ds_read_b128 v[92:95], v208 offset:16384
	ds_read_b128 v[152:155], v208 offset:18432
	s_waitcnt lgkmcnt(12)
	v_mfma_f32_32x32x16_bf16 v[48:63], v[10:13], v[120:123], v[48:63]
	v_exp_f32_e32 v136, v136
	v_exp_f32_e32 v137, v137
	v_exp_f32_e32 v138, v138
	v_exp_f32_e32 v139, v139
	ds_read_b128 v[156:159], v209 offset:16384
	ds_read_b128 v[180:183], v209 offset:18432
	s_waitcnt lgkmcnt(12)
	v_mfma_f32_32x32x16_bf16 v[64:79], v[10:13], v[124:127], v[64:79]
	v_exp_f32_e32 v140, v140
	v_exp_f32_e32 v141, v141
	v_exp_f32_e32 v142, v142
	v_exp_f32_e32 v143, v143
	ds_read_b128 v[184:187], v208 offset:20480
	ds_read_b128 v[188:191], v208 offset:22528
	s_waitcnt lgkmcnt(12)
	v_mfma_f32_32x32x16_bf16 v[48:63], v[6:9], v[148:151], v[48:63]
	v_exp_f32_e32 v96, v96
	v_exp_f32_e32 v97, v97
	v_exp_f32_e32 v98, v98
	v_exp_f32_e32 v99, v99
	ds_read_b128 v[148:151], v209 offset:20480
	ds_read_b128 v[144:147], v209 offset:22528
	s_waitcnt lgkmcnt(12)
	v_mfma_f32_32x32x16_bf16 v[64:79], v[6:9], v[80:83], v[64:79]
	v_exp_f32_e32 v100, v100
	v_exp_f32_e32 v101, v101
	v_exp_f32_e32 v102, v102
	v_exp_f32_e32 v103, v103
	s_waitcnt lgkmcnt(10)
	v_mfma_f32_32x32x16_bf16 v[48:63], v[2:5], v[84:87], v[48:63]
	v_exp_f32_e32 v104, v104
	v_exp_f32_e32 v105, v105
	v_exp_f32_e32 v106, v106
	v_exp_f32_e32 v107, v107
	s_waitcnt lgkmcnt(8)
	v_mfma_f32_32x32x16_bf16 v[64:79], v[2:5], v[88:91], v[64:79]
	v_exp_f32_e32 v108, v108
	v_exp_f32_e32 v109, v109
	v_exp_f32_e32 v110, v110
	v_exp_f32_e32 v111, v111
	s_waitcnt vmcnt(2) lgkmcnt(0)
	s_barrier
	ds_read_b64_tr_b16 v[192:193], v206 offset:40960
	ds_read_b64_tr_b16 v[194:195], v206 offset:41472
	v_add_f32_e32 v2, v128, v129
	v_add_f32_e32 v2, v130, v2
	v_add_f32_e32 v2, v131, v2
	v_add_f32_e32 v2, v132, v2
	v_add_f32_e32 v2, v133, v2
	v_cvt_pk_bf16_f32 v160, v128, v129
	v_cvt_pk_bf16_f32 v161, v130, v131
	s_waitcnt lgkmcnt(9)
	v_mfma_f32_32x32x16_bf16 v[112:127], v[92:95], v[172:175], v[32:47]
	ds_read_b64_tr_b16 v[128:129], v206 offset:45056
	ds_read_b64_tr_b16 v[130:131], v206 offset:45568
	s_waitcnt lgkmcnt(10)
	v_mfma_f32_32x32x16_bf16 v[80:95], v[152:155], v[172:175], v[32:47]
	v_add_f32_e32 v2, v134, v2
	v_add_f32_e32 v2, v135, v2
	v_add_f32_e32 v2, v136, v2
	v_add_f32_e32 v2, v137, v2
	v_cvt_pk_bf16_f32 v162, v132, v133
	v_cvt_pk_bf16_f32 v163, v134, v135
	ds_read_b64_tr_b16 v[132:133], v206 offset:41984
	ds_read_b64_tr_b16 v[134:135], v206 offset:42496
	v_add_f32_e32 v2, v138, v2
	v_add_f32_e32 v2, v139, v2
	v_add_f32_e32 v2, v140, v2
	v_add_f32_e32 v2, v141, v2
	v_cvt_pk_bf16_f32 v10, v136, v137
	v_cvt_pk_bf16_f32 v11, v138, v139
	s_waitcnt lgkmcnt(11)
	v_mfma_f32_32x32x16_bf16 v[112:127], v[156:159], v[176:179], v[112:127]
	ds_read_b64_tr_b16 v[136:137], v206 offset:46080
	ds_read_b64_tr_b16 v[138:139], v206 offset:46592
	s_waitcnt lgkmcnt(12)
	v_mfma_f32_32x32x16_bf16 v[80:95], v[180:183], v[176:179], v[80:95]
	v_add_f32_e32 v2, v142, v2
	v_add_f32_e32 v2, v143, v2
	v_add_f32_e32 v2, v96, v2
	v_add_f32_e32 v2, v97, v2
	v_cvt_pk_bf16_f32 v12, v140, v141
	v_cvt_pk_bf16_f32 v13, v142, v143
	ds_read_b64_tr_b16 v[140:141], v206 offset:43008
	ds_read_b64_tr_b16 v[142:143], v206 offset:43520
	v_add_f32_e32 v2, v98, v2
	v_add_f32_e32 v2, v99, v2
	v_add_f32_e32 v2, v100, v2
	v_add_f32_e32 v2, v101, v2
	v_cvt_pk_bf16_f32 v6, v96, v97
	v_cvt_pk_bf16_f32 v7, v98, v99
	s_waitcnt lgkmcnt(13)
	v_mfma_f32_32x32x16_bf16 v[112:127], v[184:187], v[168:171], v[112:127]
	ds_read_b64_tr_b16 v[96:97], v206 offset:47104
	ds_read_b64_tr_b16 v[98:99], v206 offset:47616
	s_waitcnt lgkmcnt(14)
	v_mfma_f32_32x32x16_bf16 v[80:95], v[188:191], v[168:171], v[80:95]
	v_add_f32_e32 v2, v102, v2
	v_add_f32_e32 v2, v103, v2
	v_add_f32_e32 v2, v104, v2
	v_add_f32_e32 v2, v105, v2
	v_cvt_pk_bf16_f32 v8, v100, v101
	v_cvt_pk_bf16_f32 v9, v102, v103
	ds_read_b64_tr_b16 v[100:101], v206 offset:44032
	ds_read_b64_tr_b16 v[102:103], v206 offset:44544
	v_add_f32_e32 v2, v106, v2
	v_add_f32_e32 v2, v107, v2
	v_add_f32_e32 v2, v108, v2
	v_add_f32_e32 v14, v109, v2
	v_cvt_pk_bf16_f32 v2, v104, v105
	v_cvt_pk_bf16_f32 v3, v106, v107
	s_waitcnt lgkmcnt(14)
	v_mfma_f32_32x32x16_bf16 v[112:127], v[148:151], v[164:167], v[112:127]
	ds_read_b64_tr_b16 v[104:105], v206 offset:48128
	ds_read_b64_tr_b16 v[106:107], v206 offset:48640
	v_mfma_f32_32x32x16_bf16 v[80:95], v[144:147], v[164:167], v[80:95]
	v_add_f32_e32 v4, v110, v14
	v_add_f32_e32 v14, v111, v4
	v_cvt_pk_bf16_f32 v4, v108, v109
	v_cvt_pk_bf16_f32 v5, v110, v111
	s_nop 0
	v_add_f32_e32 v185, v0, v14
	s_waitcnt lgkmcnt(14)
	v_mfma_f32_32x32x16_bf16 v[48:63], v[160:163], v[192:195], v[48:63]
	s_nop 0
	v_exp_f32_e32 v112, v112
	v_exp_f32_e32 v113, v113
	v_exp_f32_e32 v114, v114
	v_exp_f32_e32 v115, v115
	s_waitcnt lgkmcnt(12)
	v_mfma_f32_32x32x16_bf16 v[64:79], v[160:163], v[128:131], v[64:79]
	v_exp_f32_e32 v116, v116
	v_exp_f32_e32 v117, v117
	v_exp_f32_e32 v118, v118
	v_exp_f32_e32 v119, v119
	ds_read_b128 v[148:151], v208 offset:24576
	ds_read_b128 v[186:189], v208 offset:26624
	s_waitcnt lgkmcnt(12)
	v_mfma_f32_32x32x16_bf16 v[48:63], v[10:13], v[132:135], v[48:63]
	v_exp_f32_e32 v120, v120
	v_exp_f32_e32 v121, v121
	v_exp_f32_e32 v122, v122
	v_exp_f32_e32 v123, v123
	ds_read_b128 v[190:193], v209 offset:24576
	ds_read_b128 v[194:197], v209 offset:26624
	s_waitcnt lgkmcnt(12)
	v_mfma_f32_32x32x16_bf16 v[64:79], v[10:13], v[136:139], v[64:79]
	v_exp_f32_e32 v124, v124
	v_exp_f32_e32 v125, v125
	v_exp_f32_e32 v126, v126
	v_exp_f32_e32 v127, v127
	ds_read_b128 v[210:213], v208 offset:28672
	ds_read_b128 v[180:183], v208 offset:30720
	s_waitcnt lgkmcnt(12)
	v_mfma_f32_32x32x16_bf16 v[48:63], v[6:9], v[140:143], v[48:63]
	v_exp_f32_e32 v80, v80
	v_exp_f32_e32 v81, v81
	v_exp_f32_e32 v82, v82
	v_exp_f32_e32 v83, v83
	ds_read_b128 v[156:159], v209 offset:28672
	ds_read_b128 v[152:155], v209 offset:30720
	s_waitcnt lgkmcnt(12)
	v_mfma_f32_32x32x16_bf16 v[64:79], v[6:9], v[96:99], v[64:79]
	v_exp_f32_e32 v84, v84
	v_exp_f32_e32 v85, v85
	v_exp_f32_e32 v86, v86
	v_exp_f32_e32 v87, v87
	s_waitcnt lgkmcnt(10)
	v_mfma_f32_32x32x16_bf16 v[48:63], v[2:5], v[100:103], v[48:63]
	v_exp_f32_e32 v88, v88
	v_exp_f32_e32 v89, v89
	v_exp_f32_e32 v90, v90
	v_exp_f32_e32 v91, v91
	s_waitcnt lgkmcnt(8)
	v_mfma_f32_32x32x16_bf16 v[64:79], v[2:5], v[104:107], v[64:79]
	v_exp_f32_e32 v92, v92
	v_exp_f32_e32 v93, v93
	v_exp_f32_e32 v94, v94
	v_exp_f32_e32 v95, v95
	v_lshrrev_b32_e32 v184, 3, v203
	v_or_b32_e32 v2, s4, v184
	v_mov_b32_e32 v3, s5
	v_lshlrev_b64 v[14:15], 11, v[2:3]
	v_lshl_add_u64 v[2:3], s[48:49], 0, v[14:15]
	s_lshl_b32 s8, s26, 1
	v_and_b32_e32 v0, 56, v207
	v_lshl_add_u64 v[2:3], v[2:3], 0, s[8:9]
	v_lshlrev_b32_e32 v0, 1, v0
	v_lshl_add_u64 v[2:3], v[2:3], 0, v[0:1]
	v_add_co_u32_e32 v6, vcc, s67, v2
	s_waitcnt vmcnt(0) lgkmcnt(0)
	s_barrier
	s_nop 1
	v_addc_co_u32_e32 v7, vcc, 0, v3, vcc
	global_load_dwordx4 v[140:143], v[2:3], off
	global_load_dwordx4 v[136:139], v[6:7], off
	v_add_co_u32_e32 v6, vcc, s66, v2
	s_nop 1
	v_addc_co_u32_e32 v7, vcc, 0, v3, vcc
	v_add_co_u32_e32 v2, vcc, s63, v2
	s_nop 1
	v_addc_co_u32_e32 v3, vcc, 0, v3, vcc
	global_load_dwordx4 v[132:135], v[6:7], off
	global_load_dwordx4 v[128:131], v[2:3], off
	ds_read_b64_tr_b16 v[144:145], v206 offset:49152
	ds_read_b64_tr_b16 v[146:147], v206 offset:49664
	v_add_f32_e32 v2, v112, v113
	v_add_f32_e32 v2, v114, v2
	v_add_f32_e32 v2, v115, v2
	v_add_f32_e32 v2, v116, v2
	v_add_f32_e32 v2, v117, v2
	v_cvt_pk_bf16_f32 v160, v112, v113
	v_cvt_pk_bf16_f32 v161, v114, v115
	s_waitcnt lgkmcnt(9)
	v_mfma_f32_32x32x16_bf16 v[96:111], v[148:151], v[172:175], v[32:47]
	ds_read_b64_tr_b16 v[112:113], v206 offset:53248
	ds_read_b64_tr_b16 v[114:115], v206 offset:53760
	v_add_f32_e32 v2, v118, v2
	v_add_f32_e32 v2, v119, v2
	v_add_f32_e32 v2, v120, v2
	v_add_f32_e32 v2, v121, v2
	v_cvt_pk_bf16_f32 v162, v116, v117
	v_cvt_pk_bf16_f32 v163, v118, v119
	s_waitcnt lgkmcnt(10)
	v_mfma_f32_32x32x16_bf16 v[32:47], v[186:189], v[172:175], v[32:47]
	ds_read_b64_tr_b16 v[148:149], v206 offset:50176
	ds_read_b64_tr_b16 v[150:151], v206 offset:50688
	v_add_f32_e32 v2, v122, v2
	v_add_f32_e32 v2, v123, v2
	v_add_f32_e32 v2, v124, v2
	v_add_f32_e32 v2, v125, v2
	v_cvt_pk_bf16_f32 v10, v120, v121
	v_cvt_pk_bf16_f32 v11, v122, v123
	s_waitcnt lgkmcnt(11)
	v_mfma_f32_32x32x16_bf16 v[96:111], v[190:193], v[176:179], v[96:111]
	ds_read_b64_tr_b16 v[116:117], v206 offset:54272
	ds_read_b64_tr_b16 v[118:119], v206 offset:54784
	v_add_f32_e32 v2, v126, v2
	v_add_f32_e32 v2, v127, v2
	v_add_f32_e32 v2, v80, v2
	v_add_f32_e32 v2, v81, v2
	v_cvt_pk_bf16_f32 v12, v124, v125
	v_cvt_pk_bf16_f32 v13, v126, v127
	s_waitcnt lgkmcnt(12)
	v_mfma_f32_32x32x16_bf16 v[32:47], v[194:197], v[176:179], v[32:47]
	ds_read_b64_tr_b16 v[120:121], v206 offset:51200
	ds_read_b64_tr_b16 v[122:123], v206 offset:51712
	v_add_f32_e32 v2, v82, v2
	v_add_f32_e32 v2, v83, v2
	v_add_f32_e32 v2, v84, v2
	v_add_f32_e32 v2, v85, v2
	v_cvt_pk_bf16_f32 v6, v80, v81
	v_cvt_pk_bf16_f32 v7, v82, v83
	s_waitcnt lgkmcnt(13)
	v_mfma_f32_32x32x16_bf16 v[96:111], v[210:213], v[168:171], v[96:111]
	ds_read_b64_tr_b16 v[80:81], v206 offset:55296
	ds_read_b64_tr_b16 v[82:83], v206 offset:55808
	v_add_f32_e32 v2, v86, v2
	v_add_f32_e32 v2, v87, v2
	v_add_f32_e32 v2, v88, v2
	v_add_f32_e32 v2, v89, v2
	v_cvt_pk_bf16_f32 v8, v84, v85
	v_cvt_pk_bf16_f32 v9, v86, v87
	s_waitcnt lgkmcnt(14)
	v_mfma_f32_32x32x16_bf16 v[32:47], v[180:183], v[168:171], v[32:47]
	ds_read_b64_tr_b16 v[124:125], v206 offset:52224
	ds_read_b64_tr_b16 v[126:127], v206 offset:52736
	v_add_f32_e32 v2, v90, v2
	v_add_f32_e32 v2, v91, v2
	v_add_f32_e32 v2, v92, v2
	v_add_f32_e32 v168, v93, v2
	v_cvt_pk_bf16_f32 v2, v88, v89
	v_cvt_pk_bf16_f32 v3, v90, v91
	s_waitcnt lgkmcnt(14)
	v_mfma_f32_32x32x16_bf16 v[96:111], v[156:159], v[164:167], v[96:111]
	ds_read_b64_tr_b16 v[84:85], v206 offset:56320
	ds_read_b64_tr_b16 v[86:87], v206 offset:56832
	v_add_f32_e32 v4, v94, v168
	v_add_f32_e32 v88, v95, v4
	v_cvt_pk_bf16_f32 v4, v92, v93
	v_cvt_pk_bf16_f32 v5, v94, v95
	v_mfma_f32_32x32x16_bf16 v[32:47], v[152:155], v[164:167], v[32:47]
	s_nop 4
	v_exp_f32_e32 v96, v96
	v_exp_f32_e32 v97, v97
	v_exp_f32_e32 v98, v98
	v_exp_f32_e32 v99, v99
	s_nop 0
	v_exp_f32_e32 v100, v100
	v_exp_f32_e32 v101, v101
	v_exp_f32_e32 v102, v102
	v_exp_f32_e32 v103, v103
	s_nop 0
	v_exp_f32_e32 v104, v104
	v_exp_f32_e32 v105, v105
	v_exp_f32_e32 v106, v106
	v_exp_f32_e32 v107, v107
	s_nop 0
	v_exp_f32_e32 v108, v108
	v_exp_f32_e32 v109, v109
	v_exp_f32_e32 v110, v110
	v_exp_f32_e32 v111, v111
	v_exp_f32_e32 v32, v32
	v_exp_f32_e32 v33, v33
	v_exp_f32_e32 v34, v34
	v_exp_f32_e32 v35, v35
	s_nop 0
	v_exp_f32_e32 v36, v36
	v_exp_f32_e32 v37, v37
	v_exp_f32_e32 v38, v38
	v_exp_f32_e32 v39, v39
	s_nop 0
	v_exp_f32_e32 v40, v40
	v_exp_f32_e32 v41, v41
	v_exp_f32_e32 v42, v42
	v_exp_f32_e32 v43, v43
	s_nop 0
	v_exp_f32_e32 v44, v44
	v_exp_f32_e32 v45, v45
	v_exp_f32_e32 v46, v46
	v_exp_f32_e32 v47, v47
	s_waitcnt lgkmcnt(14)
	v_mfma_f32_32x32x16_bf16 v[48:63], v[160:163], v[144:147], v[48:63]
	v_add_f32_e32 v89, v96, v97
	v_add_f32_e32 v89, v98, v89
	v_add_f32_e32 v89, v99, v89
	v_add_f32_e32 v89, v100, v89
	v_add_f32_e32 v89, v101, v89
	v_add_f32_e32 v89, v102, v89
	v_add_f32_e32 v89, v103, v89
	s_waitcnt lgkmcnt(12)
	v_mfma_f32_32x32x16_bf16 v[64:79], v[160:163], v[112:115], v[64:79]
	v_add_f32_e32 v89, v104, v89
	v_add_f32_e32 v89, v105, v89
	v_add_f32_e32 v89, v106, v89
	v_add_f32_e32 v89, v107, v89
	v_add_f32_e32 v89, v108, v89
	v_add_f32_e32 v89, v109, v89
	v_add_f32_e32 v89, v110, v89
	s_waitcnt lgkmcnt(10)
	v_mfma_f32_32x32x16_bf16 v[48:63], v[10:13], v[148:151], v[48:63]
	v_add_f32_e32 v89, v111, v89
	v_add_f32_e32 v89, v32, v89
	v_add_f32_e32 v89, v33, v89
	v_add_f32_e32 v89, v34, v89
	v_add_f32_e32 v89, v35, v89
	v_add_f32_e32 v89, v36, v89
	v_add_f32_e32 v89, v37, v89
	s_waitcnt lgkmcnt(8)
	v_mfma_f32_32x32x16_bf16 v[64:79], v[10:13], v[116:119], v[64:79]
	v_add_f32_e32 v89, v38, v89
	v_add_f32_e32 v89, v39, v89
	v_add_f32_e32 v89, v40, v89
	v_add_f32_e32 v89, v41, v89
	v_add_f32_e32 v89, v42, v89
	v_add_f32_e32 v89, v43, v89
	v_add_f32_e32 v89, v44, v89
	s_waitcnt lgkmcnt(6)
	v_mfma_f32_32x32x16_bf16 v[48:63], v[6:9], v[120:123], v[48:63]
	v_add_f32_e32 v89, v45, v89
	v_add_f32_e32 v89, v46, v89
	v_add_f32_e32 v89, v47, v89
	v_add_f32_e32 v88, v185, v88
	v_add_f32_e32 v88, v88, v89
	v_cvt_pk_bf16_f32 v90, v96, v97
	v_cvt_pk_bf16_f32 v91, v98, v99
	s_waitcnt lgkmcnt(4)
	v_mfma_f32_32x32x16_bf16 v[64:79], v[6:9], v[80:83], v[64:79]
	v_cvt_pk_bf16_f32 v92, v100, v101
	v_cvt_pk_bf16_f32 v93, v102, v103
	v_cvt_pk_bf16_f32 v10, v104, v105
	v_cvt_pk_bf16_f32 v11, v106, v107
	v_cvt_pk_bf16_f32 v12, v108, v109
	v_cvt_pk_bf16_f32 v13, v110, v111
	v_cvt_pk_bf16_f32 v6, v32, v33
	s_waitcnt lgkmcnt(2)
	v_mfma_f32_32x32x16_bf16 v[48:63], v[2:5], v[124:127], v[48:63]
	v_cvt_pk_bf16_f32 v7, v34, v35
	v_cvt_pk_bf16_f32 v8, v36, v37
	v_cvt_pk_bf16_f32 v9, v38, v39
	v_cvt_pk_bf16_f32 v32, v40, v41
	v_cvt_pk_bf16_f32 v33, v42, v43
	v_cvt_pk_bf16_f32 v34, v44, v45
	v_cvt_pk_bf16_f32 v35, v46, v47
	s_waitcnt lgkmcnt(0)
	v_mfma_f32_32x32x16_bf16 v[64:79], v[2:5], v[84:87], v[64:79]
	v_add_u32_e32 v2, s6, v204
	v_add3_u32 v84, v2, v202, v205
	ds_read_b64_tr_b16 v[2:3],v84 offset:0
	ds_read_b64_tr_b16 v[4:5],v84 offset:512
	ds_read_b64_tr_b16 v[36:37],v84 offset:1024
	ds_read_b64_tr_b16 v[38:39],v84 offset:1536
	ds_read_b64_tr_b16 v[40:41],v84 offset:2048
	ds_read_b64_tr_b16 v[42:43],v84 offset:2560
	ds_read_b64_tr_b16 v[44:45],v84 offset:3072
	ds_read_b64_tr_b16 v[46:47],v84 offset:3584
	s_waitcnt lgkmcnt(0)
	s_nop 0
	v_mfma_f32_32x32x16_bf16 v[48:63], v[90:93], v[2:5], v[48:63]
	ds_read_b64_tr_b16 v[2:3],v84 offset:4096
	ds_read_b64_tr_b16 v[4:5],v84 offset:4608
	v_mfma_f32_32x32x16_bf16 v[48:63], v[10:13], v[36:39], v[48:63]
	ds_read_b64_tr_b16 v[36:37],v84 offset:5120
	ds_read_b64_tr_b16 v[38:39],v84 offset:5632
	v_mfma_f32_32x32x16_bf16 v[48:63], v[6:9], v[40:43], v[48:63]
	ds_read_b64_tr_b16 v[40:41],v84 offset:6144
	ds_read_b64_tr_b16 v[42:43],v84 offset:6656
	ds_read_b64_tr_b16 v[80:81],v84 offset:7168
	ds_read_b64_tr_b16 v[82:83],v84 offset:7680
	s_waitcnt lgkmcnt(0)
	v_mfma_f32_32x32x16_bf16 v[48:63], v[32:35], v[44:47], v[48:63]
	v_mfma_f32_32x32x16_bf16 v[64:79], v[90:93], v[2:5], v[64:79]
	v_mov_b32_e32 v2, v88
	s_nop 1
	v_permlane32_swap_b32_e32 v88, v2
	v_cmp_gt_u32_e32 vcc, 32, v203
	v_mfma_f32_32x32x16_bf16 v[64:79], v[10:13], v[36:39], v[64:79]
	v_mfma_f32_32x32x16_bf16 v[64:79], v[6:9], v[40:43], v[64:79]
	v_mfma_f32_32x32x16_bf16 v[64:79], v[32:35], v[80:83], v[64:79]
	s_and_saveexec_b64 s[6:7], vcc
	v_lshl_add_u32 v3, v200, 2, s31
	v_add_f32_e32 v2, v88, v2
	ds_write_b32 v3, v2 offset:128
	s_or_b64 exec, exec, s[6:7]
	s_waitcnt lgkmcnt(0)
	v_lshl_add_u32 v10, v201, 4, s31
	ds_read_b128 v[2:5], v10 offset:128
	ds_read_b128 v[6:9], v10 offset:160
	s_lshl_b32 s6, s27, 12
	s_add_i32 s6, s6, 0
	s_add_i32 s6, s6, 0x10800
	s_waitcnt lgkmcnt(1)
	v_rcp_f32_e32 v11, v2
	v_rcp_f32_e32 v12, v3
	v_rcp_f32_e32 v13, v4
	v_rcp_f32_e32 v32, v5
	s_waitcnt lgkmcnt(0)
	v_rcp_f32_e32 v33, v6
	ds_read_b128 v[2:5], v10 offset:192
	v_rcp_f32_e32 v34, v7
	v_rcp_f32_e32 v35, v8
	v_rcp_f32_e32 v36, v9
	ds_read_b128 v[6:9], v10 offset:224
	v_lshlrev_b32_e32 v10, 9, v201
	v_lshlrev_b32_e32 v37, 1, v200
	v_add3_u32 v10, s6, v10, v37
	v_mul_f32_e32 v37, v48, v11
	v_mul_f32_e32 v11, v64, v11
	v_cvt_pk_bf16_f32 v11, v11, s0
	ds_write_b16 v10, v11 offset:64
	v_mul_f32_e32 v11, v49, v12
	v_cvt_pk_bf16_f32 v11, v11, s0
	ds_write_b16 v10, v11 offset:128
	v_mul_f32_e32 v11, v65, v12
	v_cvt_pk_bf16_f32 v11, v11, s0
	ds_write_b16 v10, v11 offset:192
	v_mul_f32_e32 v11, v50, v13
	v_cvt_pk_bf16_f32 v11, v11, s0
	ds_write_b16 v10, v11 offset:256
	v_mul_f32_e32 v11, v66, v13
	v_cvt_pk_bf16_f32 v11, v11, s0
	ds_write_b16 v10, v11 offset:320
	v_mul_f32_e32 v11, v51, v32
	v_cvt_pk_bf16_f32 v11, v11, s0
	ds_write_b16 v10, v11 offset:384
	v_mul_f32_e32 v11, v67, v32
	v_cvt_pk_bf16_f32 v11, v11, s0
	ds_write_b16 v10, v11 offset:448
	v_mul_f32_e32 v11, v52, v33
	v_cvt_pk_bf16_f32 v11, v11, s0
	ds_write_b16 v10, v11 offset:1024
	v_mul_f32_e32 v11, v68, v33
	v_cvt_pk_bf16_f32 v11, v11, s0
	ds_write_b16 v10, v11 offset:1088
	v_mul_f32_e32 v11, v53, v34
	v_cvt_pk_bf16_f32 v11, v11, s0
	ds_write_b16 v10, v11 offset:1152
	v_mul_f32_e32 v11, v69, v34
	v_cvt_pk_bf16_f32 v11, v11, s0
	ds_write_b16 v10, v11 offset:1216
	v_mul_f32_e32 v11, v54, v35
	v_cvt_pk_bf16_f32 v11, v11, s0
	ds_write_b16 v10, v11 offset:1280
	v_mul_f32_e32 v11, v70, v35
	v_cvt_pk_bf16_f32 v11, v11, s0
	s_waitcnt lgkmcnt(13)
	v_rcp_f32_e32 v2, v2
	ds_write_b16 v10, v11 offset:1344
	v_mul_f32_e32 v11, v55, v36
	v_cvt_pk_bf16_f32 v11, v11, s0
	v_rcp_f32_e32 v3, v3
	ds_write_b16 v10, v11 offset:1408
	v_mul_f32_e32 v11, v71, v36
	v_cvt_pk_bf16_f32 v11, v11, s0
	ds_write_b16 v10, v11 offset:1472
	v_mul_f32_e32 v11, v56, v2
	v_mul_f32_e32 v2, v72, v2
	v_cvt_pk_bf16_f32 v2, v2, s0
	v_rcp_f32_e32 v4, v4
	ds_write_b16 v10, v2 offset:2112
	v_mul_f32_e32 v2, v57, v3
	v_cvt_pk_bf16_f32 v2, v2, s0
	ds_write_b16 v10, v2 offset:2176
	v_mul_f32_e32 v2, v73, v3
	v_cvt_pk_bf16_f32 v2, v2, s0
	v_rcp_f32_e32 v5, v5
	ds_write_b16 v10, v2 offset:2240
	v_mul_f32_e32 v2, v58, v4
	v_cvt_pk_bf16_f32 v2, v2, s0
	ds_write_b16 v10, v2 offset:2304
	v_mul_f32_e32 v2, v74, v4
	v_cvt_pk_bf16_f32 v2, v2, s0
	s_waitcnt lgkmcnt(14)
	v_rcp_f32_e32 v6, v6
	ds_write_b16 v10, v2 offset:2368
	v_mul_f32_e32 v2, v59, v5
	v_cvt_pk_bf16_f32 v2, v2, s0
	ds_write_b16 v10, v2 offset:2432
	v_mul_f32_e32 v2, v75, v5
	v_cvt_pk_bf16_f32 v2, v2, s0
	v_rcp_f32_e32 v7, v7
	ds_write_b16 v10, v2 offset:2496
	v_mul_f32_e32 v2, v60, v6
	v_cvt_pk_bf16_f32 v2, v2, s0
	ds_write_b16 v10, v2 offset:3072
	v_mul_f32_e32 v2, v76, v6
	v_cvt_pk_bf16_f32 v2, v2, s0
	v_rcp_f32_e32 v8, v8
	ds_write_b16 v10, v2 offset:3136
	v_mul_f32_e32 v2, v61, v7
	v_cvt_pk_bf16_f32 v2, v2, s0
	ds_write_b16 v10, v2 offset:3200
	v_mul_f32_e32 v2, v77, v7
	v_cvt_pk_bf16_f32 v2, v2, s0
	v_rcp_f32_e32 v9, v9
	ds_write_b16 v10, v2 offset:3264
	v_mul_f32_e32 v2, v62, v8
	v_cvt_pk_bf16_f32 v2, v2, s0
	ds_write_b16 v10, v2 offset:3328
	v_mul_f32_e32 v2, v78, v8
	v_cvt_pk_bf16_f32 v2, v2, s0
	ds_write_b16 v10, v2 offset:3392
	v_mul_f32_e32 v2, v63, v9
	s_waitcnt vmcnt(3)
	v_lshlrev_b32_e32 v12, 16, v140
	v_cvt_pk_bf16_f32 v2, v2, s0
	v_and_b32_e32 v13, 0xffff0000, v140
	v_mul_f32_e32 v4, 0xbfb8aa3b, v12
	ds_write_b16 v10, v2 offset:3456
	v_mul_f32_e32 v2, v79, v9
	v_exp_f32_e32 v8, v4
	v_mul_f32_e32 v4, 0xbfb8aa3b, v13
	v_cvt_pk_bf16_f32 v37, v37, s0
	v_cvt_pk_bf16_f32 v11, v11, s0
	v_cvt_pk_bf16_f32 v2, v2, s0
	v_add_u32_e32 v36, s6, v0
	s_add_u32 s6, s50, s8
	v_exp_f32_e32 v9, v4
	ds_write_b16 v10, v37
	ds_write_b16 v10, v11 offset:2048
	ds_write_b16 v10, v2 offset:3520
	s_addc_u32 s7, s51, 0
	s_waitcnt lgkmcnt(0)
	v_lshl_add_u64 v[2:3], s[6:7], 0, v[0:1]
	v_lshl_add_u32 v0, v184, 7, v36
	ds_read_b128 v[4:7], v0
	v_add_f32_e32 v0, 1.0, v8
	v_rcp_f32_e32 v32, v0
	v_add_f32_e32 v0, 1.0, v9
	v_rcp_f32_e32 v33, v0
	s_waitcnt lgkmcnt(0)
	v_lshlrev_b32_e32 v34, 16, v4
	v_and_b32_e32 v35, 0xffff0000, v4
	v_or_b32_e32 v0, 8, v184
	v_pk_mul_f32 v[12:13], v[32:33], v[12:13]
	v_lshlrev_b32_e32 v32, 16, v141
	v_and_b32_e32 v33, 0xffff0000, v141
	v_mul_f32_e32 v4, 0xbfb8aa3b, v32
	v_exp_f32_e32 v4, v4
	v_mul_f32_e32 v37, 0xbfb8aa3b, v33
	v_exp_f32_e32 v37, v37
	v_pk_mul_f32 v[12:13], v[12:13], v[34:35]
	v_add_f32_e32 v4, 1.0, v4
	v_rcp_f32_e32 v34, v4
	v_add_f32_e32 v4, 1.0, v37
	v_rcp_f32_e32 v35, v4
	v_cvt_pk_bf16_f32 v4, v12, v13
	v_lshlrev_b32_e32 v12, 16, v5
	v_and_b32_e32 v13, 0xffff0000, v5
	v_pk_mul_f32 v[32:33], v[34:35], v[32:33]
	v_lshlrev_b32_e32 v34, 16, v142
	v_and_b32_e32 v35, 0xffff0000, v142
	v_mul_f32_e32 v5, 0xbfb8aa3b, v34
	v_exp_f32_e32 v5, v5
	v_mul_f32_e32 v37, 0xbfb8aa3b, v35
	v_exp_f32_e32 v37, v37
	v_pk_mul_f32 v[12:13], v[32:33], v[12:13]
	v_add_f32_e32 v5, 1.0, v5
	v_rcp_f32_e32 v32, v5
	v_add_f32_e32 v5, 1.0, v37
	v_rcp_f32_e32 v33, v5
	v_cvt_pk_bf16_f32 v5, v12, v13
	v_lshlrev_b32_e32 v12, 16, v6
	v_and_b32_e32 v13, 0xffff0000, v6
	v_pk_mul_f32 v[32:33], v[32:33], v[34:35]
	v_lshlrev_b32_e32 v34, 16, v143
	v_and_b32_e32 v35, 0xffff0000, v143
	v_mul_f32_e32 v6, 0xbfb8aa3b, v34
	v_exp_f32_e32 v6, v6
	v_mul_f32_e32 v37, 0xbfb8aa3b, v35
	v_exp_f32_e32 v37, v37
	v_pk_mul_f32 v[12:13], v[32:33], v[12:13]
	v_add_f32_e32 v6, 1.0, v6
	v_rcp_f32_e32 v32, v6
	v_add_f32_e32 v6, 1.0, v37
	v_rcp_f32_e32 v33, v6
	v_cvt_pk_bf16_f32 v6, v12, v13
	v_lshlrev_b32_e32 v12, 16, v7
	v_and_b32_e32 v13, 0xffff0000, v7
	v_pk_mul_f32 v[32:33], v[32:33], v[34:35]
	v_lshl_add_u32 v8, v0, 7, v36
	v_pk_mul_f32 v[12:13], v[32:33], v[12:13]
	ds_read_b128 v[8:11], v8
	v_cvt_pk_bf16_f32 v7, v12, v13
	v_lshl_add_u64 v[12:13], v[2:3], 0, v[14:15]
	global_store_dwordx4 v[12:13], v[4:7], off
	s_waitcnt lgkmcnt(0)
	v_lshlrev_b32_e32 v14, 16, v8
	s_waitcnt vmcnt(3)
	v_lshlrev_b32_e32 v6, 16, v136
	v_and_b32_e32 v7, 0xffff0000, v136
	v_mul_f32_e32 v4, 0xbfb8aa3b, v6
	v_exp_f32_e32 v5, v4
	v_mul_f32_e32 v4, 0xbfb8aa3b, v7
	v_exp_f32_e32 v13, v4
	v_or_b32_e32 v4, s4, v0
	v_add_f32_e32 v0, 1.0, v5
	v_rcp_f32_e32 v12, v0
	v_add_f32_e32 v0, 1.0, v13
	v_rcp_f32_e32 v13, v0
	v_and_b32_e32 v15, 0xffff0000, v8
	v_mov_b32_e32 v5, s5
	v_pk_mul_f32 v[6:7], v[12:13], v[6:7]
	v_lshlrev_b32_e32 v12, 16, v137
	v_and_b32_e32 v13, 0xffff0000, v137
	v_mul_f32_e32 v0, 0xbfb8aa3b, v12
	v_exp_f32_e32 v0, v0
	v_mul_f32_e32 v8, 0xbfb8aa3b, v13
	v_exp_f32_e32 v8, v8
	v_pk_mul_f32 v[6:7], v[6:7], v[14:15]
	v_add_f32_e32 v0, 1.0, v0
	v_rcp_f32_e32 v14, v0
	v_add_f32_e32 v0, 1.0, v8
	v_rcp_f32_e32 v15, v0
	v_cvt_pk_bf16_f32 v6, v6, v7
	v_lshlrev_b32_e32 v8, 16, v9
	v_and_b32_e32 v9, 0xffff0000, v9
	v_pk_mul_f32 v[12:13], v[14:15], v[12:13]
	v_lshlrev_b32_e32 v14, 16, v138
	v_and_b32_e32 v15, 0xffff0000, v138
	v_mul_f32_e32 v0, 0xbfb8aa3b, v14
	v_exp_f32_e32 v0, v0
	v_mul_f32_e32 v7, 0xbfb8aa3b, v15
	v_exp_f32_e32 v7, v7
	v_pk_mul_f32 v[8:9], v[12:13], v[8:9]
	v_add_f32_e32 v0, 1.0, v0
	v_rcp_f32_e32 v12, v0
	v_add_f32_e32 v0, 1.0, v7
	v_rcp_f32_e32 v13, v0
	v_cvt_pk_bf16_f32 v7, v8, v9
	v_lshlrev_b32_e32 v8, 16, v10
	v_and_b32_e32 v9, 0xffff0000, v10
	v_pk_mul_f32 v[12:13], v[12:13], v[14:15]
	v_lshlrev_b32_e32 v14, 16, v139
	v_and_b32_e32 v15, 0xffff0000, v139
	v_mul_f32_e32 v0, 0xbfb8aa3b, v14
	v_exp_f32_e32 v0, v0
	v_mul_f32_e32 v10, 0xbfb8aa3b, v15
	v_exp_f32_e32 v10, v10
	v_pk_mul_f32 v[8:9], v[12:13], v[8:9]
	v_add_f32_e32 v0, 1.0, v0
	v_rcp_f32_e32 v12, v0
	v_add_f32_e32 v0, 1.0, v10
	v_rcp_f32_e32 v13, v0
	v_lshlrev_b32_e32 v10, 16, v11
	v_and_b32_e32 v11, 0xffff0000, v11
	v_cvt_pk_bf16_f32 v8, v8, v9
	v_pk_mul_f32 v[12:13], v[12:13], v[14:15]
	v_or_b32_e32 v0, 16, v184
	v_pk_mul_f32 v[10:11], v[12:13], v[10:11]
	s_waitcnt vmcnt(2)
	v_lshlrev_b32_e32 v14, 16, v132
	v_cvt_pk_bf16_f32 v9, v10, v11
	v_lshlrev_b64 v[10:11], 11, v[4:5]
	v_lshl_add_u64 v[10:11], v[2:3], 0, v[10:11]
	v_lshl_add_u32 v4, v0, 7, v36
	global_store_dwordx4 v[10:11], v[6:9], off
	ds_read_b128 v[6:9], v4
	v_and_b32_e32 v15, 0xffff0000, v132
	v_mul_f32_e32 v4, 0xbfb8aa3b, v14
	v_exp_f32_e32 v10, v4
	v_mul_f32_e32 v4, 0xbfb8aa3b, v15
	v_exp_f32_e32 v11, v4
	v_or_b32_e32 v4, s4, v0
	v_add_f32_e32 v0, 1.0, v10
	v_rcp_f32_e32 v32, v0
	v_add_f32_e32 v0, 1.0, v11
	v_rcp_f32_e32 v33, v0
	v_or_b32_e32 v0, 24, v184
	s_waitcnt lgkmcnt(0)
	v_lshlrev_b32_e32 v34, 16, v6
	v_and_b32_e32 v35, 0xffff0000, v6
	v_pk_mul_f32 v[14:15], v[32:33], v[14:15]
	v_lshlrev_b32_e32 v32, 16, v133
	v_and_b32_e32 v33, 0xffff0000, v133
	v_mul_f32_e32 v6, 0xbfb8aa3b, v32
	v_lshl_add_u32 v10, v0, 7, v36
	v_exp_f32_e32 v6, v6
	v_mul_f32_e32 v36, 0xbfb8aa3b, v33
	v_exp_f32_e32 v36, v36
	v_pk_mul_f32 v[14:15], v[14:15], v[34:35]
	v_add_f32_e32 v6, 1.0, v6
	v_rcp_f32_e32 v34, v6
	v_add_f32_e32 v6, 1.0, v36
	v_rcp_f32_e32 v35, v6
	v_cvt_pk_bf16_f32 v6, v14, v15
	v_lshlrev_b32_e32 v14, 16, v7
	v_and_b32_e32 v15, 0xffff0000, v7
	v_pk_mul_f32 v[32:33], v[34:35], v[32:33]
	v_lshlrev_b32_e32 v34, 16, v134
	v_and_b32_e32 v35, 0xffff0000, v134
	v_mul_f32_e32 v7, 0xbfb8aa3b, v34
	v_exp_f32_e32 v7, v7
	v_mul_f32_e32 v36, 0xbfb8aa3b, v35
	v_exp_f32_e32 v36, v36
	v_pk_mul_f32 v[14:15], v[32:33], v[14:15]
	v_add_f32_e32 v7, 1.0, v7
	v_rcp_f32_e32 v32, v7
	v_add_f32_e32 v7, 1.0, v36
	v_rcp_f32_e32 v33, v7
	v_cvt_pk_bf16_f32 v7, v14, v15
	v_lshlrev_b32_e32 v14, 16, v8
	v_and_b32_e32 v15, 0xffff0000, v8
	v_pk_mul_f32 v[32:33], v[32:33], v[34:35]
	v_lshlrev_b32_e32 v34, 16, v135
	v_and_b32_e32 v35, 0xffff0000, v135
	v_mul_f32_e32 v8, 0xbfb8aa3b, v34
	v_exp_f32_e32 v8, v8
	v_mul_f32_e32 v36, 0xbfb8aa3b, v35
	v_exp_f32_e32 v36, v36
	v_pk_mul_f32 v[14:15], v[32:33], v[14:15]
	v_add_f32_e32 v8, 1.0, v8
	v_rcp_f32_e32 v32, v8
	v_add_f32_e32 v8, 1.0, v36
	v_rcp_f32_e32 v33, v8
	v_cvt_pk_bf16_f32 v8, v14, v15
	v_lshlrev_b32_e32 v14, 16, v9
	v_and_b32_e32 v15, 0xffff0000, v9
	v_pk_mul_f32 v[32:33], v[32:33], v[34:35]
	ds_read_b128 v[10:13], v10
	v_pk_mul_f32 v[14:15], v[32:33], v[14:15]
	s_waitcnt vmcnt(2)
	v_lshlrev_b32_e32 v32, 16, v128
	v_cvt_pk_bf16_f32 v9, v14, v15
	v_lshlrev_b64 v[14:15], 11, v[4:5]
	v_and_b32_e32 v33, 0xffff0000, v128
	v_mul_f32_e32 v4, 0xbfb8aa3b, v32
	v_exp_f32_e32 v4, v4
	v_mul_f32_e32 v34, 0xbfb8aa3b, v33
	v_exp_f32_e32 v34, v34
	v_lshl_add_u64 v[14:15], v[2:3], 0, v[14:15]
	v_add_f32_e32 v4, 1.0, v4
	global_store_dwordx4 v[14:15], v[6:9], off
	v_lshlrev_b32_e32 v14, 16, v129
	v_and_b32_e32 v15, 0xffff0000, v129
	v_rcp_f32_e32 v6, v4
	v_add_f32_e32 v4, 1.0, v34
	v_rcp_f32_e32 v7, v4
	v_or_b32_e32 v4, s4, v0
	v_mul_f32_e32 v0, 0xbfb8aa3b, v14
	s_waitcnt lgkmcnt(0)
	v_lshlrev_b32_e32 v8, 16, v10
	v_and_b32_e32 v9, 0xffff0000, v10
	v_exp_f32_e32 v0, v0
	v_mul_f32_e32 v10, 0xbfb8aa3b, v15
	v_exp_f32_e32 v10, v10
	v_pk_mul_f32 v[6:7], v[6:7], v[32:33]
	v_add_f32_e32 v0, 1.0, v0
	v_pk_mul_f32 v[6:7], v[6:7], v[8:9]
	v_rcp_f32_e32 v8, v0
	v_add_f32_e32 v0, 1.0, v10
	v_rcp_f32_e32 v9, v0
	v_cvt_pk_bf16_f32 v6, v6, v7
	v_lshlrev_b32_e32 v10, 16, v11
	v_and_b32_e32 v11, 0xffff0000, v11
	v_pk_mul_f32 v[8:9], v[8:9], v[14:15]
	v_lshlrev_b32_e32 v14, 16, v130
	v_and_b32_e32 v15, 0xffff0000, v130
	v_mul_f32_e32 v0, 0xbfb8aa3b, v14
	v_exp_f32_e32 v0, v0
	v_mul_f32_e32 v7, 0xbfb8aa3b, v15
	v_exp_f32_e32 v7, v7
	v_pk_mul_f32 v[8:9], v[8:9], v[10:11]
	v_add_f32_e32 v0, 1.0, v0
	v_rcp_f32_e32 v10, v0
	v_add_f32_e32 v0, 1.0, v7
	v_rcp_f32_e32 v11, v0
	v_cvt_pk_bf16_f32 v7, v8, v9
	v_lshlrev_b32_e32 v8, 16, v12
	v_and_b32_e32 v9, 0xffff0000, v12
	v_pk_mul_f32 v[10:11], v[10:11], v[14:15]
	v_lshlrev_b32_e32 v14, 16, v131
	v_and_b32_e32 v15, 0xffff0000, v131
	v_mul_f32_e32 v0, 0xbfb8aa3b, v14
	v_exp_f32_e32 v0, v0
	v_mul_f32_e32 v12, 0xbfb8aa3b, v15
	v_exp_f32_e32 v12, v12
	v_pk_mul_f32 v[8:9], v[10:11], v[8:9]
	v_add_f32_e32 v0, 1.0, v0
	v_rcp_f32_e32 v10, v0
	v_add_f32_e32 v0, 1.0, v12
	v_rcp_f32_e32 v11, v0
	v_lshlrev_b32_e32 v12, 16, v13
	v_and_b32_e32 v13, 0xffff0000, v13
	v_lshlrev_b64 v[4:5], 11, v[4:5]
	v_pk_mul_f32 v[10:11], v[10:11], v[14:15]
	v_cvt_pk_bf16_f32 v8, v8, v9
	v_pk_mul_f32 v[10:11], v[10:11], v[12:13]
	v_lshl_add_u64 v[2:3], v[2:3], 0, v[4:5]
	v_cvt_pk_bf16_f32 v9, v10, v11
	global_store_dwordx4 v[2:3], v[6:9], off
	s_waitcnt vmcnt(0) lgkmcnt(0)
	s_barrier
	s_mov_b64 s[4:5], 0

.LBB0_1708:
	s_cmp_lt_i32 s34, 9
	s_cselect_b64 s[0:1], -1, 0
	s_cmp_gt_i32 s35, 8
	s_cselect_b64 s[4:5], -1, 0
	s_and_b64 s[0:1], s[0:1], s[4:5]
	s_andn2_b64 vcc, exec, s[0:1]
	s_cbranch_vccnz .LBB0_1787
	s_bfe_u32 s98, s2, 0x30005
	s_mul_i32 s99, s98, 150
	s_cmp_eq_u32 s98, 0
	s_cbranch_scc1 .LBB0_1713
	s_memrealtime s[100:101]
	s_waitcnt lgkmcnt(0)
	s_mov_b32 s98, s100
.LBB0_1712:
	s_sleep 8
	s_memrealtime s[100:101]
	s_waitcnt lgkmcnt(0)
	s_sub_u32 s100, s100, s98
	s_cmp_lt_u32 s100, s99
	s_cbranch_scc1 .LBB0_1712
